# clean variant: only gate phase rewrite + convert rewrite on top of baseline
# speedup vs baseline: 1.0032x; 1.0030x over previous
; DI int otid() { int t = threadIdx.x; asm volatile("" : "+v"(t)); return t; }
; DI void gla_out_phase(const Params& P, LAS unsigned char* lds, int lj) {
;     ...
;   for (int item = blockIdx.x; item < 8 * NSEG; item += gridDim.x) {
;     const int seg = item % NSEG, bh = item / NSEG;
;     {
;       const int tid = otid(), wid = tid >> 6, lane = tid & 63, fr = lane & 15, fq = lane >> 4;
;       f32x4 accS[8][2]; float dprod = 1.f;
;       gla_load_state(state + ((size_t)(bh * 2 + 0) * NSEG + seg) * 32768 + wid * 4096 + lane, lds, accS, wid, fr, fq);
;       gla_walk<1>(P, lds, lj, bh >> 2, bh & 3, 0, seg, accS, dprod);
;     }
;     asm volatile("s_waitcnt vmcnt(0)" ::: "memory");
;     __syncthreads();
;     asm volatile("buffer_inv sc1" ::: "memory");
;     {
;       const int tid = otid(), wid = tid >> 6, lane = tid & 63, fr = lane & 15, fq = lane >> 4;
;       f32x4 accS[8][2]; float dprod = 1.f;
;       gla_load_state(state + ((size_t)(bh * 2 + 1) * NSEG + seg) * 32768 + wid * 4096 + lane, lds, accS, wid, fr, fq);
;       gla_walk<2>(P, lds, lj, bh >> 2, bh & 3, 1, seg, accS, dprod);
;     }
;     __syncthreads();
;   }
.LBB0_185:
	s_waitcnt lgkmcnt(0)
	s_barrier
	s_add_i32 s62, s62, s10
	v_readlane_b32 s18, v253, 40
	s_cmpk_gt_i32 s62, 0xff
	v_readlane_b32 s19, v253, 41
	s_waitcnt lgkmcnt(0)
	s_barrier
	s_cbranch_scc1 .LBB0_216

; #define LAS __attribute__((address_space(3)))
; DI f32x4 mfma16(bf16x8 a, bf16x8 b, f32x4 c) { return __builtin_amdgcn_mfma_f32_16x16x32_bf16(a, b, c, 0, 0, 0); }
; template <int MODE>
; DI void gla_walk(const Params& P, LAS unsigned char* lds, int lj, int b, int h, int dir, int seg, f32x4 (&accS)[8][2], float& dprod) {
;     ...
;     GL_LOAD((cc + 1 < CPS) ? cc + 1 : cc);
;     unsigned long long pof[2][4]; u32x2 prv[2][4];
;     if (MODE == 2) {
; #pragma unroll
;       for (int tt = 0; tt < 4; ++tt)
; #pragma unroll
;         for (int et2 = 0; et2 < 2; ++et2)
;           prv[et2][tt] = *(const u32x2*)(rbase + (unsigned)((c0 + 63 - (tt * 16 + fr)) * 3072 + (2 * wid + et2) * 16 + 4 * fq));
; #pragma unroll
;       for (int tt = 0; tt < 4; ++tt)
; #pragma unroll
;         for (int et2 = 0; et2 < 2; ++et2)
;           pof[et2][tt] = *(const unsigned long long*)(gbase + (unsigned)((c0 + 63 - (tt * 16 + fr)) * DM + (2 * wid + et2) * 16 + 4 * fq));
;     }
;     if (MODE != 0) {
;       const int st = wid >> 1;
; #pragma unroll
;       for (int t2 = 0; t2 < 2; ++t2) {
;         const int tt = 2 * (wid & 1) + t2;
;         f32x4 a = (f32x4){0.f, 0.f, 0.f, 0.f};
;         if (st <= tt) {
; #pragma unroll
;           for (int ks = 0; ks < 4; ++ks)
;             a = mfma16(*(const LAS bf16x8*)(lds + GL_K + (st * 16 + fr) * GL_QS + ks * 64 + fq * 16),
;                        *(const LAS bf16x8*)(lds + GL_Q + (tt * 16 + fr) * GL_QS + ks * 64 + fq * 16), a);
;           const int tcol = tt * 16 + fr;
; #pragma unroll
;           for (int r = 0; r < 4; ++r) { const int s = st * 16 + 4 * fq + r; const bool keep = dir ? (s < tcol) : (s <= tcol); a[r] = keep ? a[r] : 0.f; }
;         }
.LBB0_204:
	s_or_b64 exec, exec, s[18:19]
	s_cmp_lg_u32 s47, 0xfff90000
	s_cselect_b32 s18, s54, -7
	s_add_i32 s18, s18, s50
	v_mov_b32_e32 v106, v220
	s_lshl_b32 s19, s18, 6
	s_waitcnt lgkmcnt(0)
	s_barrier
	s_or_b32 s19, s19, 63
	v_lshlrev_b32_e32 v90, 3, v106
	v_lshrrev_b32_e32 v0, 4, v106
	v_and_b32_e32 v82, 0x78, v90
	v_sub_u32_e32 v0, s19, v0
	v_lshl_or_b32 v0, v0, 9, v82
	v_add_u32_e32 v92, 0x200, v106
	v_lshlrev_b64 v[74:75], 1, v[0:1]
	v_lshrrev_b32_e32 v0, 4, v92
	v_sub_u32_e32 v0, s19, v0
	v_lshl_or_b32 v0, v0, 9, v82
	v_lshlrev_b64 v[82:83], 1, v[0:1]
	v_lshrrev_b32_e32 v0, 5, v106
	v_sub_u32_e32 v0, s19, v0
	v_and_b32_e32 v100, 0xf8, v90
	v_mul_lo_u32 v0, v0, s35
	v_or_b32_e32 v0, v0, v100
	v_lshl_add_u64 v[90:91], v[0:1], 1, s[14:15]
	v_lshrrev_b32_e32 v0, 5, v92
	v_sub_u32_e32 v0, s19, v0
	v_mul_lo_u32 v0, v0, s35
	v_or_b32_e32 v0, v0, v100
	v_lshl_add_u64 v[92:93], v[0:1], 1, s[14:15]
	v_add_u32_e32 v0, 0x400, v106
	v_lshrrev_b32_e32 v0, 5, v0
	v_sub_u32_e32 v0, s19, v0
	v_mul_lo_u32 v0, v0, s35
	v_or_b32_e32 v0, v0, v100
	v_lshl_add_u64 v[98:99], v[0:1], 1, s[14:15]
	v_add_u32_e32 v0, 0x600, v106
	v_lshrrev_b32_e32 v0, 5, v0
	v_sub_u32_e32 v0, s19, v0
	v_mul_lo_u32 v0, v0, s35
	v_ashrrev_i32_e32 v70, 6, v72
	v_bfe_u32 v68, v72, 4, 2
	v_or_b32_e32 v0, v0, v100
	v_and_b32_e32 v66, 15, v72
	v_lshl_add_u64 v[100:101], v[0:1], 1, s[14:15]
	v_and_b32_e32 v0, 0x7f, v106
	v_lshlrev_b32_e32 v123, 5, v70
	v_lshlrev_b32_e32 v203, 2, v68
	v_lshlrev_b32_e32 v110, 2, v0
	v_or_b32_e32 v112, v123, v203
	v_mul_u32_u24_e32 v0, 0xc00, v66
	v_sub_u32_e32 v0, v112, v0
	s_ashr_i32 s19, s18, 31
	v_add_u32_e32 v111, s52, v0
	s_lshl_b64 s[18:19], s[18:19], 11
	v_add_u32_e32 v0, 0x17f400, v111
	s_add_u32 s18, s36, s18
	v_lshl_add_u64 v[106:107], v[0:1], 1, s[40:41]
	v_add_u32_e32 v0, 0x173400, v111
	v_lshl_add_u64 v[76:77], s[44:45], 0, v[74:75]
	v_lshl_add_u64 v[78:79], s[42:43], 0, v[74:75]
	v_lshl_add_u64 v[84:85], s[44:45], 0, v[82:83]
	v_lshl_add_u64 v[86:87], s[42:43], 0, v[82:83]
	s_addc_u32 s19, s37, s19
	v_lshl_add_u64 v[108:109], v[0:1], 1, s[40:41]
	v_add_u32_e32 v0, 0x167400, v111
	global_load_dwordx4 v[74:77], v[76:77], off
	s_nop 0
	global_load_dwordx4 v[78:81], v[78:79], off
	s_nop 0
	global_load_dwordx4 v[82:85], v[84:85], off
	s_nop 0
	global_load_dwordx4 v[86:89], v[86:87], off
	s_nop 0
	global_load_dwordx4 v[94:97], v[90:91], off
	s_nop 0
	global_load_dwordx4 v[90:93], v[92:93], off
	s_nop 0
	global_load_dwordx4 v[102:105], v[98:99], off
	s_nop 0
	global_load_dwordx4 v[98:101], v[100:101], off
	s_nop 0
	global_load_dword v202, v110, s[18:19]
	global_load_dwordx2 v[184:185], v[106:107], off
	global_load_dwordx2 v[182:183], v[106:107], off offset:32
	global_load_dwordx2 v[178:179], v[108:109], off
	v_lshl_add_u64 v[106:107], v[0:1], 1, s[40:41]
	v_add_u32_e32 v0, 0x15b400, v111
	v_lshl_add_u64 v[110:111], v[0:1], 1, s[40:41]
	v_lshlrev_b32_e32 v0, 10, v66
	v_sub_u32_e32 v0, v112, v0
	s_add_i32 s18, s51, s47
	global_load_dwordx2 v[176:177], v[108:109], off offset:32
	global_load_dwordx2 v[172:173], v[106:107], off
	global_load_dwordx2 v[170:171], v[106:107], off offset:32
	global_load_dwordx2 v[166:167], v[110:111], off
	global_load_dwordx2 v[164:165], v[110:111], off offset:32
	v_add_u32_e32 v106, s18, v0
	v_add_u32_e32 v0, 0x7fc00, v106
	v_lshl_add_u64 v[180:181], v[0:1], 1, s[0:1]
	v_add_u32_e32 v0, 0x7bc00, v106
	v_lshl_add_u64 v[174:175], v[0:1], 1, s[0:1]
	v_add_u32_e32 v0, 0x77c00, v106
	v_lshl_add_u64 v[168:169], v[0:1], 1, s[0:1]
	v_add_u32_e32 v0, 0x73c00, v106
	global_load_dwordx2 v[200:201], v[180:181], off
	global_load_dwordx2 v[198:199], v[180:181], off offset:32
	global_load_dwordx2 v[196:197], v[174:175], off
	global_load_dwordx2 v[194:195], v[174:175], off offset:32
	v_lshl_add_u64 v[162:163], v[0:1], 1, s[0:1]
	global_load_dwordx2 v[192:193], v[168:169], off
	global_load_dwordx2 v[190:191], v[168:169], off offset:32
	global_load_dwordx2 v[188:189], v[162:163], off
	global_load_dwordx2 v[186:187], v[162:163], off offset:32
	v_ashrrev_i32_e32 v110, 7, v72
	v_lshlrev_b32_e32 v0, 1, v70
	v_and_b32_e32 v111, 2, v0
	v_lshlrev_b32_e32 v0, 4, v110
	v_or_b32_e32 v70, v0, v66
	v_mul_lo_u32 v70, v70, s65
	v_add_u32_e32 v70, s68, v70
	v_lshlrev_b32_e32 v204, 4, v68
	v_or_b32_e32 v106, v203, v0
	v_add_u32_e32 v122, s61, v204
	v_cmp_le_i32_e32 vcc, v110, v111
	v_lshl_or_b32 v113, v111, 4, v66
	v_mov_b32_e32 v109, 0
	v_add_u32_e32 v108, v70, v204
	v_or_b32_e32 v107, 1, v106
	v_or_b32_e32 v70, 2, v106
	v_or_b32_e32 v0, 3, v106
	v_mov_b32_e32 v114, 0
	v_mov_b32_e32 v115, 0
	v_mov_b32_e32 v116, 0
	v_mov_b32_e32 v117, 0
	s_and_saveexec_b64 s[18:19], vcc
	s_cbranch_execz .LBB0_206
	v_mad_u32_u24 v112, v113, s65, v122
	ds_read_b128 v[114:117], v108
	ds_read_b128 v[118:121], v112
	v_cmp_lt_i32_e32 vcc, v106, v113
	s_waitcnt lgkmcnt(0)
	v_mfma_f32_16x16x32_bf16 v[114:117], v[114:117], v[118:121], 0
	ds_read_b128 v[118:121], v108 offset:64
	ds_read_b128 v[124:127], v112 offset:64
	s_waitcnt lgkmcnt(0)
	v_mfma_f32_16x16x32_bf16 v[114:117], v[118:121], v[124:127], v[114:117]
	ds_read_b128 v[118:121], v108 offset:128
	ds_read_b128 v[124:127], v112 offset:128
	s_waitcnt lgkmcnt(0)
	v_mfma_f32_16x16x32_bf16 v[114:117], v[118:121], v[124:127], v[114:117]
	ds_read_b128 v[118:121], v108 offset:192
	ds_read_b128 v[124:127], v112 offset:192
	s_waitcnt lgkmcnt(0)
	v_mfma_f32_16x16x32_bf16 v[114:117], v[118:121], v[124:127], v[114:117]
	s_nop 7
	v_cndmask_b32_e32 v114, 0, v114, vcc
	v_cmp_lt_i32_e32 vcc, v107, v113
	s_nop 1
	v_cndmask_b32_e32 v115, 0, v115, vcc
	v_cmp_lt_i32_e32 vcc, v70, v113
	s_nop 1
	v_cndmask_b32_e32 v116, 0, v116, vcc
	v_cmp_lt_i32_e32 vcc, v0, v113
	s_nop 1
	v_cndmask_b32_e32 v117, 0, v117, vcc

; #define LAS __attribute__((address_space(3)))
; DI unsigned cvt_pk(float lo, float hi) { unsigned r; asm("v_cvt_pk_bf16_f32 %0, %1, %2" : "=v"(r) : "v"(lo), "v"(hi)); return r; }
; DI f32x4 mfma16(bf16x8 a, bf16x8 b, f32x4 c) { return __builtin_amdgcn_mfma_f32_16x16x32_bf16(a, b, c, 0, 0, 0); }
; #define LBAR do { asm volatile("s_waitcnt lgkmcnt(0)" ::: "memory"); __builtin_amdgcn_s_barrier(); asm volatile("" ::: "memory"); } while (0)
; template <int MODE>
; DI void gla_walk(const Params& P, LAS unsigned char* lds, int lj, int b, int h, int dir, int seg, f32x4 (&accS)[8][2], float& dprod) {
;     ...
;         u32x2 w; w.x = cvt_pk(a[0], a[1]); w.y = cvt_pk(a[2], a[3]);
;         *(LAS u32x2*)(lds + GL_A + (tt * 16 + fr) * GL_AS + (st * 16 + 4 * fq) * 2) = w;
;       }
;       LBAR;
;     }
;     bf16x8 vf[2][2];
; #pragma unroll
;     for (int et2 = 0; et2 < 2; ++et2)
; #pragma unroll
;       for (int ks = 0; ks < 2; ++ks) {
;         LAS unsigned char* p = lds + GL_V + (ks * 32 + 8 * fq + (fr >> 2)) * GL_VS + ((2 * wid + et2) * 16 + 4 * (fr & 3)) * 2;
;         vf[et2][ks] = tr_pair(p, p + 4 * GL_VS);
;       }
;     if (MODE != 0) {
;       f32x4 accO[2][4];
; #pragma unroll
;       for (int et2 = 0; et2 < 2; ++et2)
; #pragma unroll
;         for (int tt = 0; tt < 4; ++tt) accO[et2][tt] = (f32x4){0.f, 0.f, 0.f, 0.f};
; #pragma unroll
;       for (int tt = 0; tt < 4; ++tt) {
; #pragma unroll
;         for (int ks = 0; ks < 2; ++ks) {
;           const bf16x8 af = *(const LAS bf16x8*)(lds + GL_A + (tt * 16 + fr) * GL_AS + ks * 64 + fq * 16);
;           accO[0][tt] = mfma16(vf[0][ks], af, accO[0][tt]);
;           accO[1][tt] = mfma16(vf[1][ks], af, accO[1][tt]);
;         }
; #pragma unroll
;         for (int ks = 0; ks < 4; ++ks) {
;           const bf16x8 qf = *(const LAS bf16x8*)(lds + GL_Q + (tt * 16 + fr) * GL_QS + ks * 64 + fq * 16);
; #pragma unroll
;           for (int et2 = 0; et2 < 2; ++et2) {
;             const bf16x8 sf = *(const LAS bf16x8*)(lds + GL_ST + ((2 * wid + et2) * 16 + fr) * GL_STS + ks * 64 + fq * 16);
;             accO[et2][tt] = mfma16(sf, qf, accO[et2][tt]);
;           }
;         }
.LBB0_208:
	s_or_b64 exec, exec, s[18:19]
	v_mad_u32_u24 v0, v110, s11, v112
	v_cvt_pk_bf16_f32 v106, v109, v111
	v_cvt_pk_bf16_f32 v107, v113, v114
	ds_write_b64 v0, v[106:107]
	v_lshrrev_b32_e32 v0, 2, v66
	v_or_b32_e32 v206, v205, v0
	v_and_b32_e32 v70, 0xffffffc0, v72
	v_lshlrev_b32_e32 v0, 3, v72
	v_and_b32_e32 v207, 24, v0
	v_add_u32_e32 v0, s64, v70
	v_mul_u32_u24_e32 v72, 0x220, v206
	s_waitcnt lgkmcnt(0)
	s_barrier
	v_add3_u32 v0, v0, v207, v72
	ds_read_b64_tr_b16 v[112:113], v0 offset:2176
	ds_read_b64_tr_b16 v[110:111], v0
	ds_read_b64_tr_b16 v[114:115], v0 offset:32
	ds_read_b64_tr_b16 v[106:107], v0 offset:17408
	ds_read_b64_tr_b16 v[108:109], v0 offset:19584
	ds_read_b64_tr_b16 v[116:117], v0 offset:2208
	ds_read_b64_tr_b16 v[118:119], v0 offset:17440
	ds_read_b64_tr_b16 v[120:121], v0 offset:19616
	v_or_b32_e32 v0, v123, v66
	v_mul_u32_u24_e32 v123, 0x90, v66
	v_add3_u32 v154, s53, v204, v123
	ds_read_b128 v[124:127], v154
	ds_read_b128 v[132:135], v154 offset:64
	s_waitcnt lgkmcnt(1)
	v_mfma_f32_16x16x32_bf16 v[128:131], v[110:113], v[124:127], 0
	v_mul_lo_u32 v0, v0, s65
	v_mad_u32_u24 v156, v66, s65, v122
	v_add3_u32 v72, 0, v204, v0
	v_mfma_f32_16x16x32_bf16 v[124:127], v[114:117], v[124:127], 0
	s_waitcnt lgkmcnt(0)
	v_mfma_f32_16x16x32_bf16 v[128:131], v[106:109], v[132:135], v[128:131]
	v_mfma_f32_16x16x32_bf16 v[124:127], v[118:121], v[132:135], v[124:127]
	ds_read_b128 v[132:135], v156
	ds_read_b128 v[136:139], v72
	s_waitcnt lgkmcnt(0)
	v_mfma_f32_16x16x32_bf16 v[128:131], v[136:139], v[132:135], v[128:131]
	ds_read_b128 v[136:139], v72 offset:4352
	s_waitcnt lgkmcnt(0)
	v_mfma_f32_16x16x32_bf16 v[122:125], v[136:139], v[132:135], v[124:127]
	ds_read_b128 v[132:135], v156 offset:64
	ds_read_b128 v[136:139], v72 offset:64
	s_waitcnt lgkmcnt(0)
	v_mfma_f32_16x16x32_bf16 v[126:129], v[136:139], v[132:135], v[128:131]
	ds_read_b128 v[136:139], v72 offset:4416
	s_waitcnt lgkmcnt(0)
	v_mfma_f32_16x16x32_bf16 v[122:125], v[136:139], v[132:135], v[122:125]
	ds_read_b128 v[130:133], v156 offset:128
	ds_read_b128 v[134:137], v72 offset:128
	s_waitcnt lgkmcnt(0)
	v_mfma_f32_16x16x32_bf16 v[126:129], v[134:137], v[130:133], v[126:129]
	ds_read_b128 v[134:137], v72 offset:4480
	s_waitcnt lgkmcnt(0)
	v_mfma_f32_16x16x32_bf16 v[130:133], v[134:137], v[130:133], v[122:125]
	ds_read_b128 v[134:137], v156 offset:192
	s_nop 1
	ds_read_b128 v[122:125], v72 offset:192
	s_waitcnt lgkmcnt(0)
	v_mfma_f32_16x16x32_bf16 v[122:125], v[122:125], v[134:137], v[126:129]
	s_nop 2
	ds_read_b128 v[126:129], v72 offset:4544
	s_waitcnt lgkmcnt(0)
	v_mfma_f32_16x16x32_bf16 v[126:129], v[126:129], v[134:137], v[130:133]
	s_nop 2
	ds_read_b128 v[130:133], v154 offset:2304
	ds_read_b128 v[138:141], v154 offset:2368
	s_waitcnt lgkmcnt(1)
	v_mfma_f32_16x16x32_bf16 v[134:137], v[110:113], v[130:133], 0
	v_mfma_f32_16x16x32_bf16 v[130:133], v[114:117], v[130:133], 0
	s_waitcnt lgkmcnt(0)
	v_mfma_f32_16x16x32_bf16 v[134:137], v[106:109], v[138:141], v[134:137]
	v_mfma_f32_16x16x32_bf16 v[130:133], v[118:121], v[138:141], v[130:133]
	ds_read_b128 v[138:141], v156 offset:4352
	ds_read_b128 v[142:145], v72
	s_waitcnt lgkmcnt(0)
	v_mfma_f32_16x16x32_bf16 v[134:137], v[142:145], v[138:141], v[134:137]
	ds_read_b128 v[142:145], v72 offset:4352
	s_waitcnt lgkmcnt(0)
	v_mfma_f32_16x16x32_bf16 v[130:133], v[142:145], v[138:141], v[130:133]
	ds_read_b128 v[138:141], v156 offset:4416
	ds_read_b128 v[142:145], v72 offset:64
	s_waitcnt lgkmcnt(0)
	v_mfma_f32_16x16x32_bf16 v[134:137], v[142:145], v[138:141], v[134:137]
	ds_read_b128 v[142:145], v72 offset:4416
	s_waitcnt lgkmcnt(0)
	v_mfma_f32_16x16x32_bf16 v[130:133], v[142:145], v[138:141], v[130:133]
	ds_read_b128 v[138:141], v156 offset:4480
	ds_read_b128 v[142:145], v72 offset:128
	s_waitcnt lgkmcnt(0)
	v_mfma_f32_16x16x32_bf16 v[134:137], v[142:145], v[138:141], v[134:137]
	ds_read_b128 v[142:145], v72 offset:4480
	s_waitcnt lgkmcnt(0)
	v_mfma_f32_16x16x32_bf16 v[138:141], v[142:145], v[138:141], v[130:133]
	ds_read_b128 v[142:145], v156 offset:4544
	s_nop 1
	ds_read_b128 v[130:133], v72 offset:192
	s_waitcnt lgkmcnt(0)
	v_mfma_f32_16x16x32_bf16 v[130:133], v[130:133], v[142:145], v[134:137]
	s_nop 2
	ds_read_b128 v[134:137], v72 offset:4544
	s_waitcnt lgkmcnt(0)
	v_mfma_f32_16x16x32_bf16 v[134:137], v[134:137], v[142:145], v[138:141]
	s_nop 2
	ds_read_b128 v[138:141], v154 offset:4608
	ds_read_b128 v[146:149], v154 offset:4672
	s_waitcnt lgkmcnt(1)
	v_mfma_f32_16x16x32_bf16 v[142:145], v[110:113], v[138:141], 0
	v_mfma_f32_16x16x32_bf16 v[138:141], v[114:117], v[138:141], 0
	s_waitcnt lgkmcnt(0)
	v_mfma_f32_16x16x32_bf16 v[142:145], v[106:109], v[146:149], v[142:145]
	v_mfma_f32_16x16x32_bf16 v[138:141], v[118:121], v[146:149], v[138:141]
	ds_read_b128 v[146:149], v156 offset:8704
	ds_read_b128 v[150:153], v72
	s_waitcnt lgkmcnt(0)
	v_mfma_f32_16x16x32_bf16 v[142:145], v[150:153], v[146:149], v[142:145]
	ds_read_b128 v[150:153], v72 offset:4352
	s_waitcnt lgkmcnt(0)
	v_mfma_f32_16x16x32_bf16 v[138:141], v[150:153], v[146:149], v[138:141]
	ds_read_b128 v[146:149], v156 offset:8768
	ds_read_b128 v[150:153], v72 offset:64
	s_waitcnt lgkmcnt(0)
	v_mfma_f32_16x16x32_bf16 v[142:145], v[150:153], v[146:149], v[142:145]
	ds_read_b128 v[150:153], v72 offset:4416
	s_waitcnt lgkmcnt(0)
	v_mfma_f32_16x16x32_bf16 v[138:141], v[150:153], v[146:149], v[138:141]
	ds_read_b128 v[146:149], v156 offset:8832
	ds_read_b128 v[150:153], v72 offset:128
	s_waitcnt lgkmcnt(0)
	v_mfma_f32_16x16x32_bf16 v[142:145], v[150:153], v[146:149], v[142:145]
	ds_read_b128 v[150:153], v72 offset:4480
	s_waitcnt lgkmcnt(0)
; #define LAS __attribute__((address_space(3)))
; DI unsigned cvt_pk(float lo, float hi) { unsigned r; asm("v_cvt_pk_bf16_f32 %0, %1, %2" : "=v"(r) : "v"(lo), "v"(hi)); return r; }
; template <int MODE>
; DI void gla_walk(const Params& P, LAS unsigned char* lds, int lj, int b, int h, int dir, int seg, f32x4 (&accS)[8][2], float& dprod) {
;     ...
;       for (int tt = 0; tt < 4; ++tt) {
; #pragma unroll
;         for (int ks = 0; ks < 2; ++ks) {
;           const bf16x8 af = *(const LAS bf16x8*)(lds + GL_A + (tt * 16 + fr) * GL_AS + ks * 64 + fq * 16);
;           accO[0][tt] = mfma16(vf[0][ks], af, accO[0][tt]);
;           accO[1][tt] = mfma16(vf[1][ks], af, accO[1][tt]);
;         }
; #pragma unroll
;         for (int ks = 0; ks < 4; ++ks) {
;           const bf16x8 qf = *(const LAS bf16x8*)(lds + GL_Q + (tt * 16 + fr) * GL_QS + ks * 64 + fq * 16);
; #pragma unroll
;           for (int et2 = 0; et2 < 2; ++et2) {
;             const bf16x8 sf = *(const LAS bf16x8*)(lds + GL_ST + ((2 * wid + et2) * 16 + fr) * GL_STS + ks * 64 + fq * 16);
;             accO[et2][tt] = mfma16(sf, qf, accO[et2][tt]);
;           }
;         }
;         SCHED;
;       }
;       if (MODE == 1) {
; #pragma unroll
;         for (int tt = 0; tt < 4; ++tt) {
;           const int t = tt * 16 + fr, tok = c0 + t;
; #pragma unroll
;           for (int et2 = 0; et2 < 2; ++et2) {
;             u32x2 w; w.x = cvt_pk(accO[et2][tt][0], accO[et2][tt][1]); w.y = cvt_pk(accO[et2][tt][2], accO[et2][tt][3]);
;             *(u32x2*)(gbase + (unsigned)(tok * DM + (2 * wid + et2) * 16 + 4 * fq)) = w;
;           }
;         }
;       } else {
; #pragma unroll
;         for (int tt = 0; tt < 4; ++tt) {
;           const int t = tt * 16 + fr;
;           float q = 0.f;
; #pragma unroll
;           for (int et2 = 0; et2 < 2; ++et2) {
;             const unsigned long long pvv = pof[et2][tt];
;             const unsigned lo = (unsigned)pvv, hi = (unsigned)(pvv >> 32);
;             f32x4 o = accO[et2][tt];
;             o[0] += __uint_as_float(lo << 16); o[1] += __uint_as_float(lo & 0xffff0000u); o[2] += __uint_as_float(hi << 16); o[3] += __uint_as_float(hi & 0xffff0000u);
;             accO[et2][tt] = o;
;             q += o[0] * o[0] + o[1] * o[1] + o[2] * o[2] + o[3] * o[3];
;           }
;           q += __shfl_xor(q, 16); q += __shfl_xor(q, 32);
;           if (fq == 0) RED[wid * 64 + t] = q;
;         }
	v_mfma_f32_16x16x32_bf16 v[146:149], v[150:153], v[146:149], v[138:141]
	ds_read_b128 v[150:153], v156 offset:8896
	s_nop 1
	ds_read_b128 v[138:141], v72 offset:192
	s_waitcnt lgkmcnt(0)
	v_mfma_f32_16x16x32_bf16 v[138:141], v[138:141], v[150:153], v[142:145]
	s_nop 2
	ds_read_b128 v[142:145], v72 offset:4544
	s_waitcnt lgkmcnt(0)
	v_mfma_f32_16x16x32_bf16 v[142:145], v[142:145], v[150:153], v[146:149]
	s_nop 2
	ds_read_b128 v[146:149], v154 offset:6912
	ds_read_b128 v[208:211], v154 offset:6976
	s_waitcnt lgkmcnt(1)
	v_mfma_f32_16x16x32_bf16 v[150:153], v[110:113], v[146:149], 0
	v_mfma_f32_16x16x32_bf16 v[146:149], v[114:117], v[146:149], 0
	s_waitcnt lgkmcnt(0)
	v_mfma_f32_16x16x32_bf16 v[150:153], v[106:109], v[208:211], v[150:153]
	v_mfma_f32_16x16x32_bf16 v[146:149], v[118:121], v[208:211], v[146:149]
	ds_read_b128 v[208:211], v156 offset:13056
	ds_read_b128 v[212:215], v72
	s_waitcnt lgkmcnt(0)
	v_mfma_f32_16x16x32_bf16 v[150:153], v[212:215], v[208:211], v[150:153]
	ds_read_b128 v[212:215], v72 offset:4352
	s_waitcnt lgkmcnt(0)
	v_mfma_f32_16x16x32_bf16 v[146:149], v[212:215], v[208:211], v[146:149]
	ds_read_b128 v[208:211], v156 offset:13120
	ds_read_b128 v[212:215], v72 offset:64
	s_waitcnt lgkmcnt(0)
	v_mfma_f32_16x16x32_bf16 v[150:153], v[212:215], v[208:211], v[150:153]
	ds_read_b128 v[212:215], v72 offset:4416
	s_waitcnt lgkmcnt(0)
	v_mfma_f32_16x16x32_bf16 v[146:149], v[212:215], v[208:211], v[146:149]
	ds_read_b128 v[208:211], v156 offset:13184
	ds_read_b128 v[212:215], v72 offset:128
	s_waitcnt lgkmcnt(0)
	v_mfma_f32_16x16x32_bf16 v[150:153], v[212:215], v[208:211], v[150:153]
	ds_read_b128 v[212:215], v72 offset:4480
	s_waitcnt lgkmcnt(0)
	v_mfma_f32_16x16x32_bf16 v[208:211], v[212:215], v[208:211], v[146:149]
	ds_read_b128 v[212:215], v156 offset:13248
	s_nop 1
	ds_read_b128 v[146:149], v72 offset:192
	s_waitcnt lgkmcnt(0)
	v_mfma_f32_16x16x32_bf16 v[146:149], v[146:149], v[212:215], v[150:153]
	s_nop 2
	ds_read_b128 v[150:153], v72 offset:4544
	s_waitcnt lgkmcnt(0)
	v_mfma_f32_16x16x32_bf16 v[150:153], v[150:153], v[212:215], v[208:211]
	v_and_b32_e32 v154, 64, v224
	v_xor_b32_e32 v72, 16, v224
	v_add_u32_e32 v154, 64, v154
	v_cmp_lt_i32_e32 vcc, v72, v154
	v_readlane_b32 s16, v254, 33
	s_nop 0
	v_cndmask_b32_e32 v72, v224, v72, vcc
	v_lshlrev_b32_e32 v211, 2, v72
	v_xor_b32_e32 v72, 32, v224
	v_cmp_lt_i32_e32 vcc, v72, v154
	s_nop 1
	v_cndmask_b32_e32 v72, v224, v72, vcc
	v_cmp_eq_u32_e32 vcc, 0, v68
	v_lshlrev_b32_e32 v68, 2, v70
	v_lshlrev_b32_e32 v70, 2, v66
	v_add3_u32 v210, s16, v68, v70
	s_waitcnt vmcnt(7)
	v_lshlrev_b32_e32 v68, 16, v200
	s_waitcnt vmcnt(6)
	v_lshlrev_b32_e32 v70, 16, v198
	v_add_f32_e32 v156, v122, v68
	v_and_b32_e32 v68, 0xffff0000, v200
	v_add_f32_e32 v160, v126, v70
	v_and_b32_e32 v70, 0xffff0000, v198
	v_add_f32_e32 v209, v123, v68
	v_add_f32_e32 v70, v127, v70
	v_lshlrev_b32_e32 v212, 2, v72
	v_lshlrev_b32_e32 v68, 16, v201
	v_mul_f32_e32 v122, v209, v209
	v_lshlrev_b32_e32 v72, 16, v199
	v_mul_f32_e32 v123, v70, v70
	v_add_f32_e32 v154, v124, v68
	v_and_b32_e32 v68, 0xffff0000, v201
	v_fmac_f32_e32 v122, v156, v156
	v_add_f32_e32 v158, v128, v72
	v_and_b32_e32 v72, 0xffff0000, v199
	v_fmac_f32_e32 v123, v160, v160
	v_add_f32_e32 v68, v125, v68
	v_fmac_f32_e32 v122, v154, v154
	v_add_f32_e32 v72, v129, v72
	v_fmac_f32_e32 v123, v158, v158
	v_fmac_f32_e32 v122, v68, v68
	v_fmac_f32_e32 v123, v72, v72
	v_add_f32_e32 v122, v122, v123
	ds_bpermute_b32 v123, v211, v122
	s_waitcnt lgkmcnt(0)
	v_add_f32_e32 v122, v122, v123
	ds_bpermute_b32 v123, v212, v122
	s_and_saveexec_b64 s[18:19], vcc
	s_cbranch_execz .LBB0_210
	s_waitcnt lgkmcnt(0)
	v_add_f32_e32 v122, v122, v123
	ds_write_b32 v210, v122
; template <int MODE>
; DI void gla_walk(const Params& P, LAS unsigned char* lds, int lj, int b, int h, int dir, int seg, f32x4 (&accS)[8][2], float& dprod) {
;     ...
;         for (int tt = 0; tt < 4; ++tt) {
;           const int t = tt * 16 + fr;
;           float q = 0.f;
; #pragma unroll
;           for (int et2 = 0; et2 < 2; ++et2) {
;             const unsigned long long pvv = pof[et2][tt];
;             const unsigned lo = (unsigned)pvv, hi = (unsigned)(pvv >> 32);
;             f32x4 o = accO[et2][tt];
;             o[0] += __uint_as_float(lo << 16); o[1] += __uint_as_float(lo & 0xffff0000u); o[2] += __uint_as_float(hi << 16); o[3] += __uint_as_float(hi & 0xffff0000u);
;             accO[et2][tt] = o;
;             q += o[0] * o[0] + o[1] * o[1] + o[2] * o[2] + o[3] * o[3];
;           }
;           q += __shfl_xor(q, 16); q += __shfl_xor(q, 32);
;           if (fq == 0) RED[wid * 64 + t] = q;
;         }
.LBB0_210:
	s_or_b64 exec, exec, s[18:19]
	s_waitcnt vmcnt(5)
	v_lshlrev_b32_e32 v122, 16, v196
	v_add_f32_e32 v208, v130, v122
	v_and_b32_e32 v122, 0xffff0000, v196
	s_waitcnt vmcnt(4) lgkmcnt(0)
	v_lshlrev_b32_e32 v123, 16, v194
	v_add_f32_e32 v201, v131, v122
	v_lshlrev_b32_e32 v122, 16, v197
	v_add_f32_e32 v198, v134, v123
	v_and_b32_e32 v123, 0xffff0000, v194
	v_add_f32_e32 v200, v132, v122
	v_and_b32_e32 v122, 0xffff0000, v197
	v_add_f32_e32 v197, v135, v123
	v_lshlrev_b32_e32 v123, 16, v195
	v_add_f32_e32 v196, v136, v123
	v_and_b32_e32 v123, 0xffff0000, v195
	v_add_f32_e32 v199, v133, v122
	v_mul_f32_e32 v122, v201, v201
	v_add_f32_e32 v194, v137, v123
	v_mul_f32_e32 v123, v197, v197
	v_fmac_f32_e32 v122, v208, v208
	v_fmac_f32_e32 v123, v198, v198
	v_fmac_f32_e32 v122, v200, v200
	v_fmac_f32_e32 v123, v196, v196
	v_fmac_f32_e32 v122, v199, v199
	v_fmac_f32_e32 v123, v194, v194
	v_add_f32_e32 v122, v122, v123
	ds_bpermute_b32 v123, v211, v122
	s_waitcnt lgkmcnt(0)
	v_add_f32_e32 v122, v122, v123
	ds_bpermute_b32 v123, v212, v122
	s_and_saveexec_b64 s[18:19], vcc
	s_cbranch_execz .LBB0_212
	s_waitcnt lgkmcnt(0)
	v_add_f32_e32 v122, v122, v123
	ds_write_b32 v210, v122 offset:64
.LBB0_212:
	s_or_b64 exec, exec, s[18:19]
	s_waitcnt vmcnt(3)
	v_lshlrev_b32_e32 v122, 16, v192
	s_waitcnt vmcnt(2) lgkmcnt(0)
	v_lshlrev_b32_e32 v123, 16, v190
	v_add_f32_e32 v138, v138, v122
	v_and_b32_e32 v122, 0xffff0000, v192
	v_add_f32_e32 v134, v142, v123
	v_and_b32_e32 v123, 0xffff0000, v190
	v_add_f32_e32 v137, v139, v122
	v_lshlrev_b32_e32 v122, 16, v193
	v_add_f32_e32 v133, v143, v123
	v_lshlrev_b32_e32 v123, 16, v191
	v_add_f32_e32 v136, v140, v122
	v_and_b32_e32 v122, 0xffff0000, v193
	v_add_f32_e32 v131, v144, v123
	v_and_b32_e32 v123, 0xffff0000, v191
	v_add_f32_e32 v135, v141, v122
	v_mul_f32_e32 v122, v137, v137
	v_add_f32_e32 v130, v145, v123
	v_mul_f32_e32 v123, v133, v133
	v_fmac_f32_e32 v122, v138, v138
	v_fmac_f32_e32 v123, v134, v134
	v_fmac_f32_e32 v122, v136, v136
	v_fmac_f32_e32 v123, v131, v131
	v_fmac_f32_e32 v122, v135, v135
	v_fmac_f32_e32 v123, v130, v130
	v_add_f32_e32 v122, v122, v123
	ds_bpermute_b32 v123, v211, v122
	s_waitcnt lgkmcnt(0)
	v_add_f32_e32 v122, v122, v123
	ds_bpermute_b32 v123, v212, v122
	s_and_saveexec_b64 s[18:19], vcc
	s_cbranch_execz .LBB0_214
	s_waitcnt lgkmcnt(0)
	v_add_f32_e32 v122, v122, v123
	ds_write_b32 v210, v122 offset:128
.LBB0_214:
	s_or_b64 exec, exec, s[18:19]
	s_waitcnt vmcnt(1)
	v_lshlrev_b32_e32 v122, 16, v188
	v_add_f32_e32 v129, v146, v122
	v_and_b32_e32 v122, 0xffff0000, v188
	v_add_f32_e32 v128, v147, v122
	v_lshlrev_b32_e32 v122, 16, v189
	v_add_f32_e32 v127, v148, v122
	v_and_b32_e32 v122, 0xffff0000, v189
	v_add_f32_e32 v126, v149, v122
	s_waitcnt vmcnt(0)
	v_lshlrev_b32_e32 v122, 16, v186
	v_add_f32_e32 v125, v150, v122
	v_and_b32_e32 v122, 0xffff0000, v186
	v_add_f32_e32 v124, v151, v122
	v_mul_f32_e32 v132, v128, v128
	v_lshlrev_b32_e32 v122, 16, v187
	v_mul_f32_e32 v139, v124, v124
	v_fmac_f32_e32 v132, v129, v129
	s_waitcnt lgkmcnt(0)
	v_add_f32_e32 v123, v152, v122
	v_and_b32_e32 v122, 0xffff0000, v187
	v_fmac_f32_e32 v139, v125, v125
	v_fmac_f32_e32 v132, v127, v127
	v_add_f32_e32 v122, v153, v122
	v_fmac_f32_e32 v139, v123, v123
	v_fmac_f32_e32 v132, v126, v126
	v_fmac_f32_e32 v139, v122, v122
	v_add_f32_e32 v132, v132, v139
	ds_bpermute_b32 v139, v211, v132
	s_waitcnt lgkmcnt(0)
	v_add_f32_e32 v132, v132, v139
	ds_bpermute_b32 v139, v212, v132
	s_and_saveexec_b64 s[18:19], vcc
	s_cbranch_execz .LBB0_201
	s_waitcnt lgkmcnt(0)
	v_add_f32_e32 v132, v132, v139
	ds_write_b32 v210, v132 offset:192
	s_branch .LBB0_201

; DI void attn_phase(const Params& P, LAS unsigned char* lds, int b) {
;     ...
;         if (rd + 1 < nrounds) AT_LOAD(rd + 1);
.LBB0_321:
	s_andn2_b64 vcc, exec, s[0:1]
	s_cbranch_vccnz .LBB0_335
	s_add_i32 s13, s61, 0x100
	s_lshl_b32 s14, s20, s67
	s_and_b64 s[0:1], s[36:37], exec
	v_mov_b32_e32 v0, s29
	v_cmp_le_i32_e32 vcc, s29, v117
	s_cselect_b32 s0, s13, s66
	s_cselect_b32 s13, 0, s14
	v_cndmask_b32_e32 v0, 0, v0, vcc
	s_sub_i32 s14, s0, 64
	v_sub_u32_e32 v0, v117, v0
	v_add_u32_e32 v0, s14, v0
	v_mov_b32_e32 v40, v1
	v_mov_b32_e32 v41, v1
	v_mov_b32_e32 v3, v1
	v_cmp_lt_i32_e64 s[0:1], -1, v0
	v_cmp_gt_i32_e64 s[48:49], s28, v0
	v_mov_b32_e32 v42, v1
	v_mov_b32_e32 v43, v1
	v_mov_b64_e32 v[32:33], v[40:41]
	v_mov_b64_e32 v[36:37], v[40:41]
	v_lshl_add_u64 v[106:107], s[94:95], 0, v[2:3]
	v_lshl_add_u64 v[108:109], s[82:83], 0, v[2:3]
	s_and_b64 s[46:47], s[0:1], s[48:49]
	v_mov_b64_e32 v[34:35], v[42:43]
	v_mov_b64_e32 v[38:39], v[42:43]
	s_and_saveexec_b64 s[0:1], s[46:47]
	s_cbranch_execz .LBB0_324
	v_cndmask_b32_e64 v2, 0, 1, vcc
	v_lshlrev_b32_e32 v0, s34, v0
	v_add3_u32 v0, s13, v2, v0
	v_lshlrev_b64 v[2:3], 7, v[0:1]
	v_lshl_add_u64 v[32:33], v[106:107], 0, v[2:3]
	v_lshl_add_u64 v[2:3], v[108:109], 0, v[2:3]
	global_load_dwordx4 v[32:35], v[32:33], off
	s_nop 0
	global_load_dwordx4 v[36:39], v[2:3], off
.LBB0_324:
	s_or_b64 exec, exec, s[0:1]
	v_mov_b32_e32 v0, s29
	v_cmp_le_i32_e32 vcc, s29, v116
	v_mov_b64_e32 v[46:47], v[42:43]
	v_mov_b64_e32 v[44:45], v[40:41]
	v_cndmask_b32_e32 v0, 0, v0, vcc
	v_sub_u32_e32 v0, v116, v0
	v_add_u32_e32 v0, s14, v0
	v_cmp_lt_i32_e64 s[0:1], -1, v0
	v_cmp_gt_i32_e64 s[48:49], s28, v0
	s_and_b64 s[46:47], s[0:1], s[48:49]
	s_and_saveexec_b64 s[0:1], s[46:47]
	s_cbranch_execz .LBB0_326
	v_cndmask_b32_e64 v2, 0, 1, vcc
	v_lshlrev_b32_e32 v0, s34, v0
	v_add3_u32 v0, s13, v2, v0
	v_lshlrev_b64 v[2:3], 7, v[0:1]
	v_lshl_add_u64 v[40:41], v[106:107], 0, v[2:3]
	v_lshl_add_u64 v[2:3], v[108:109], 0, v[2:3]
	global_load_dwordx4 v[40:43], v[40:41], off
	s_nop 0
	global_load_dwordx4 v[44:47], v[2:3], off
.LBB0_326:
	s_or_b64 exec, exec, s[0:1]
	v_mov_b32_e32 v0, s29
	v_cmp_le_i32_e32 vcc, s29, v115
	v_mov_b32_e32 v2, v1
	v_mov_b32_e32 v3, v1
	v_cndmask_b32_e32 v0, 0, v0, vcc
	v_sub_u32_e32 v0, v115, v0
	v_add_u32_e32 v60, s14, v0
	v_cmp_lt_i32_e64 s[0:1], -1, v60
	v_cmp_gt_i32_e64 s[48:49], s28, v60
	v_mov_b32_e32 v0, v1
	v_mov_b64_e32 v[50:51], v[2:3]
	v_mov_b64_e32 v[54:55], v[2:3]
	s_and_b64 s[46:47], s[0:1], s[48:49]
	v_mov_b64_e32 v[48:49], v[0:1]
	v_mov_b64_e32 v[52:53], v[0:1]
	s_and_saveexec_b64 s[0:1], s[46:47]
	s_cbranch_execz .LBB0_328
	v_cndmask_b32_e64 v48, 0, 1, vcc
	v_lshlrev_b32_e32 v49, s34, v60
	v_add3_u32 v48, s13, v48, v49
	v_mov_b32_e32 v49, v1
	v_lshlrev_b64 v[48:49], 7, v[48:49]
	v_lshl_add_u64 v[50:51], v[106:107], 0, v[48:49]
	v_lshl_add_u64 v[52:53], v[108:109], 0, v[48:49]
	global_load_dwordx4 v[48:51], v[50:51], off
	s_nop 0
	global_load_dwordx4 v[52:55], v[52:53], off
.LBB0_328:
	s_or_b64 exec, exec, s[0:1]
	v_mov_b32_e32 v60, s29
	v_cmp_le_i32_e32 vcc, s29, v113
	v_mov_b64_e32 v[66:67], v[2:3]
	v_mov_b64_e32 v[64:65], v[0:1]
	v_cndmask_b32_e32 v60, 0, v60, vcc
	v_sub_u32_e32 v60, v113, v60
	v_add_u32_e32 v68, s14, v60
	v_cmp_lt_i32_e64 s[0:1], -1, v68
	v_cmp_gt_i32_e64 s[48:49], s28, v68
	v_mov_b64_e32 v[62:63], v[2:3]
	s_and_b64 s[46:47], s[0:1], s[48:49]
	v_mov_b64_e32 v[60:61], v[0:1]
	s_and_saveexec_b64 s[0:1], s[46:47]
	s_cbranch_execz .LBB0_330
	v_cndmask_b32_e64 v0, 0, 1, vcc
	v_lshlrev_b32_e32 v2, s34, v68
	v_add3_u32 v0, s13, v0, v2
	v_lshlrev_b64 v[2:3], 7, v[0:1]
	v_lshl_add_u64 v[60:61], v[106:107], 0, v[2:3]
	v_lshl_add_u64 v[2:3], v[108:109], 0, v[2:3]
	global_load_dwordx4 v[60:63], v[60:61], off
	s_nop 0
	global_load_dwordx4 v[64:67], v[2:3], off
.LBB0_330:
	s_or_b64 exec, exec, s[0:1]
	v_mov_b32_e32 v0, s29
	v_cmp_le_i32_e32 vcc, s29, v112
	v_mov_b32_e32 v2, v1
	v_mov_b32_e32 v3, v1
	v_cndmask_b32_e32 v0, 0, v0, vcc
	v_sub_u32_e32 v0, v112, v0
	v_add_u32_e32 v80, s14, v0
	v_cmp_lt_i32_e64 s[0:1], -1, v80
	v_cmp_gt_i32_e64 s[48:49], s28, v80
	v_mov_b32_e32 v0, v1
	v_mov_b64_e32 v[70:71], v[2:3]
	v_mov_b64_e32 v[74:75], v[2:3]
	s_and_b64 s[46:47], s[0:1], s[48:49]
	v_mov_b64_e32 v[68:69], v[0:1]
	v_mov_b64_e32 v[72:73], v[0:1]
	s_and_saveexec_b64 s[0:1], s[46:47]
	s_cbranch_execz .LBB0_332
	v_cndmask_b32_e64 v0, 0, 1, vcc
	v_lshlrev_b32_e32 v2, s34, v80
	v_add3_u32 v0, s13, v0, v2
	v_lshlrev_b64 v[2:3], 7, v[0:1]
	v_lshl_add_u64 v[68:69], v[106:107], 0, v[2:3]
	v_lshl_add_u64 v[2:3], v[108:109], 0, v[2:3]
	global_load_dwordx4 v[68:71], v[68:69], off
	s_nop 0
	global_load_dwordx4 v[72:75], v[2:3], off
.LBB0_332:
	s_or_b64 exec, exec, s[0:1]
	v_mov_b32_e32 v0, s29
	v_cmp_le_i32_e32 vcc, s29, v105
	v_mov_b32_e32 v87, 0
	v_mov_b32_e32 v86, 0
	v_cndmask_b32_e32 v0, 0, v0, vcc
	v_sub_u32_e32 v0, v105, v0
	v_add_u32_e32 v0, s14, v0
	v_cmp_lt_i32_e64 s[0:1], -1, v0
	v_cmp_gt_i32_e64 s[48:49], s28, v0
	s_and_b64 s[14:15], s[0:1], s[48:49]
	v_mov_b32_e32 v85, 0
	v_mov_b32_e32 v84, 0
	v_mov_b32_e32 v83, 0
	v_mov_b32_e32 v82, 0
	v_mov_b32_e32 v81, 0
	v_mov_b32_e32 v80, 0
	s_and_saveexec_b64 s[0:1], s[14:15]
	s_cbranch_execz .LBB0_334
	v_cndmask_b32_e64 v2, 0, 1, vcc
	v_lshlrev_b32_e32 v0, s34, v0
	v_add3_u32 v0, s13, v2, v0
	v_lshlrev_b64 v[2:3], 7, v[0:1]
	v_lshl_add_u64 v[80:81], v[106:107], 0, v[2:3]
	v_lshl_add_u64 v[2:3], v[108:109], 0, v[2:3]
	global_load_dwordx4 v[80:83], v[80:81], off
	s_nop 0
	global_load_dwordx4 v[84:87], v[2:3], off

; #define LAS __attribute__((address_space(3)))
; DI f32x4 mfma16(bf16x8 a, bf16x8 b, f32x4 c) { return __builtin_amdgcn_mfma_f32_16x16x32_bf16(a, b, c, 0, 0, 0); }
; DI void attn_phase(const Params& P, LAS unsigned char* lds, int b) {
;     ...
;         LAS unsigned char* kb = lds + (rowbase + fr) * AT_STR + fq * 16;
;         LAS unsigned char* vb = lds + AT_VOFF + (rowbase + fq * 4 + (fr >> 2)) * AT_STR + (fr & 3) * 8;
;         f32x4 sc[2][9];
; #pragma unroll
;         for (int t = 0; t < 10; ++t) {
;           const bf16x8 k0 = *(const LAS bf16x8*)(kb + t * 16 * AT_STR), k1 = *(const LAS bf16x8*)(kb + t * 16 * AT_STR + 64);
;           if (t < 9) { f32x4 a = (f32x4){0.f, 0.f, 0.f, 0.f}; a = mfma16(k0, qf[0][0], a); a = mfma16(k1, qf[0][1], a); sc[0][t] = a; }
;           if (t > 0 && NQ == 2) { f32x4 a = (f32x4){0.f, 0.f, 0.f, 0.f}; a = mfma16(k0, qf[1][0], a); a = mfma16(k1, qf[1][1], a); sc[1][t - 1] = a; }
.LBB0_335:
	v_mad_i32_i24 v180, v110, s29, v111
	v_or_b32_e32 v0, v180, v177
	v_mul_lo_u32 v0, v0, s11
	v_add_u32_e32 v0, 0, v0
	v_add_u32_e32 v0, v0, v104
	ds_read_b128 v[104:107], v0 offset:64
	ds_read_b128 v[108:111], v0
	v_lshlrev_b32_e32 v179, 2, v145
	s_and_b64 vcc, exec, s[44:45]
	s_waitcnt vmcnt(1) lgkmcnt(0)
	v_mfma_f32_16x16x32_bf16 v[108:111], v[108:111], v[92:95], 0
	s_waitcnt vmcnt(0)
	v_mfma_f32_16x16x32_bf16 v[132:135], v[104:107], v[88:91], v[108:111]
	s_nop 5
	ds_read_b128 v[108:111], v0 offset:2304
	ds_read_b128 v[112:115], v0 offset:2368
	s_waitcnt lgkmcnt(1)
	v_mfma_f32_16x16x32_bf16 v[104:107], v[108:111], v[92:95], 0
	s_waitcnt lgkmcnt(0)
	v_mfma_f32_16x16x32_bf16 v[104:107], v[112:115], v[88:91], v[104:107]
	s_cbranch_vccnz .LBB0_337
	v_mfma_f32_16x16x32_bf16 v[56:59], v[108:111], v[100:103], 0
	v_mfma_f32_16x16x32_bf16 v[56:59], v[112:115], v[96:99], v[56:59]

; #define LAS __attribute__((address_space(3)))
;   DI void operator()(LAS unsigned char* lds, f32x4 (&acc)[2][2][4][2], int pm, int pn, int wr, int wc, int fr, int fq) const {
;     ...
;     for (int aim = 0; aim < 4; ++aim) {
;       const int ai = aim >> 1, mb = (aim & 1) * 2;
;       f32x4 cs[4][2], sn[4][2];
;       if (type < 2) {
; #pragma unroll
;         for (int m = mb; m < mb + 2; ++m)
; #pragma unroll
;           for (int n = 0; n < 2; ++n) {
;             if (aim == 0) {
;               const int tr = wr * 32 + m * 16 + fr;
;               cs[m][n] = *(const LAS f32x4*)(lds + EQ_CS + tr * EQ_CSS + (8 * fq + 4 * n) * 4);
;               sn[m][n] = *(const LAS f32x4*)(lds + EQ_CS + tr * EQ_CSS + 128 + (8 * fq + 4 * n) * 4);
;             } else {
;               const size_t o = (size_t)(s0 + ai * HALF + m * 16) * 32 + 8 * fq + 4 * n;
;               cs[m][n] = *(const f32x4*)(cosT + o); sn[m][n] = *(const f32x4*)(sinT + o);
;             }
;           }
;       }
.LBB0_468:
	v_cndmask_b32_e64 v70, 0, 1, s[36:37]
	v_cmp_ne_u32_e64 s[44:45], 1, v70
	s_andn2_b64 vcc, exec, s[36:37]
	s_cbranch_vccnz .LBB0_470
	v_lshl_or_b32 v70, v231, 5, v219
	v_mul_lo_u32 v70, v70, s65
	v_readlane_b32 s17, v254, 34
	s_nop 1
	v_add3_u32 v70, s17, v70, v180
	ds_read_b128 v[134:137], v70
	ds_read_b128 v[114:117], v70 offset:16
	ds_read_b128 v[142:145], v70 offset:128
	ds_read_b128 v[130:133], v70 offset:144
	ds_read_b128 v[90:93], v70 offset:4480
	ds_read_b128 v[74:77], v70 offset:4496
	ds_read_b128 v[82:85], v70 offset:4352
	ds_read_b128 v[70:73], v70 offset:4368

; #define LAS __attribute__((address_space(3)))
; DI unsigned cvt_pk(float lo, float hi) { unsigned r; asm("v_cvt_pk_bf16_f32 %0, %1, %2" : "=v"(r) : "v"(lo), "v"(hi)); return r; }
;   DI void operator()(LAS unsigned char* lds, f32x4 (&acc)[2][2][4][2], int pm, int pn, int wr, int wc, int fr, int fq) const {
;     ...
;       if (type < 2) {
; #pragma unroll
;         for (int m = mb; m < mb + 2; ++m)
; #pragma unroll
;           for (int n = 0; n < 2; ++n) {
;             if (aim == 0) {
;               const int tr = wr * 32 + m * 16 + fr;
;               cs[m][n] = *(const LAS f32x4*)(lds + EQ_CS + tr * EQ_CSS + (8 * fq + 4 * n) * 4);
;               sn[m][n] = *(const LAS f32x4*)(lds + EQ_CS + tr * EQ_CSS + 128 + (8 * fq + 4 * n) * 4);
;             } else {
;               const size_t o = (size_t)(s0 + ai * HALF + m * 16) * 32 + 8 * fq + 4 * n;
;               cs[m][n] = *(const f32x4*)(cosT + o); sn[m][n] = *(const f32x4*)(sinT + o);
;             }
;           }
;       }
;       EPI_FENCE;
; #pragma unroll
;       for (int m = mb; m < mb + 2; ++m) {
;         const int s = s0 + ai * HALF + m * 16;
;         f32x4 v[2][2];
; #pragma unroll
;         for (int bj = 0; bj < 2; ++bj)
; #pragma unroll
;           for (int n = 0; n < 2; ++n) v[bj][n] = acc[ai][bj][m][n] * rstd[ai][m];
;         if (type < 2) {
;           float q = 0.f;
; #pragma unroll
;           for (int bj = 0; bj < 2; ++bj)
; #pragma unroll
;             for (int n = 0; n < 2; ++n) q += v[bj][n][0] * v[bj][n][0] + v[bj][n][1] * v[bj][n][1] + v[bj][n][2] * v[bj][n][2] + v[bj][n][3] * v[bj][n][3];
;           q += __shfl_xor(q, 16); q += __shfl_xor(q, 32);
;           float rn = rsqrtf(q * (1.0f / 64.0f) + EPS);
;           if (type == 0) rn *= 0.125f * LOG2E;
; #pragma unroll
;           for (int n = 0; n < 2; ++n) {
;             const f32x4 x1 = v[0][n] * g1[n] * rn, x2 = v[1][n] * g2[n] * rn;
;             v[0][n] = x1 * cs[m][n] - x2 * sn[m][n]; v[1][n] = x2 * cs[m][n] + x1 * sn[m][n];
;           }
;         }
;         bf16_t* rp = base + (size_t)s * 64 + 8 * fq;
; #pragma unroll
;         for (int bj = 0; bj < 2; ++bj) {
;           u32x4 w; w.x = cvt_pk(v[bj][0][0], v[bj][0][1]); w.y = cvt_pk(v[bj][0][2], v[bj][0][3]); w.z = cvt_pk(v[bj][1][0], v[bj][1][1]); w.w = cvt_pk(v[bj][1][2], v[bj][1][3]);
;           *(u32x4*)(rp + bj * 32) = w;
;         }
.LBB0_474:
	v_or_b32_e32 v88, 16, v182
	v_ashrrev_i32_e32 v89, 31, v88
	v_lshlrev_b64 v[88:89], 7, v[88:89]
	v_lshl_add_u64 v[88:89], v[180:181], 0, v[88:89]
	v_cvt_pk_bf16_f32 v96, v98, v99
	v_cvt_pk_bf16_f32 v97, v80, v81
	v_cvt_pk_bf16_f32 v98, v100, v101
	v_cvt_pk_bf16_f32 v99, v68, v69
	global_store_dwordx4 v[88:89], v[96:99], off
	v_cvt_pk_bf16_f32 v94, v94, v95
	v_cvt_pk_bf16_f32 v95, v66, v67
	v_lshlrev_b32_e32 v0, 3, v218
	v_or_b32_e32 v190, 32, v182
	v_cvt_pk_bf16_f32 v96, v86, v87
	v_cvt_pk_bf16_f32 v97, v78, v79
	global_store_dwordx4 v[88:89], v[94:97], off offset:64
	v_or_b32_e32 v188, 48, v182
	s_and_b64 vcc, exec, s[44:45]
	v_ashrrev_i32_e32 v191, 31, v190
	v_lshlrev_b32_e32 v0, 2, v0
	v_ashrrev_i32_e32 v189, 31, v188
	s_cbranch_vccnz .LBB0_476
	v_lshlrev_b64 v[66:67], 7, v[190:191]
	v_readlane_b32 s18, v254, 8
	v_readlane_b32 s20, v254, 10
	v_lshlrev_b64 v[78:79], 7, v[188:189]
	v_or_b32_e32 v66, v66, v0
	v_readlane_b32 s19, v254, 9
	v_readlane_b32 s21, v254, 11
	v_or_b32_e32 v78, v78, v0
	v_lshl_add_u64 v[68:69], s[18:19], 0, v[66:67]
	v_lshl_add_u64 v[66:67], s[20:21], 0, v[66:67]
	v_lshl_add_u64 v[80:81], s[18:19], 0, v[78:79]
	v_lshl_add_u64 v[94:95], s[20:21], 0, v[78:79]
	global_load_dwordx4 v[98:101], v[68:69], off offset:16
	global_load_dwordx4 v[126:129], v[68:69], off
	global_load_dwordx4 v[122:125], v[66:67], off offset:16
	global_load_dwordx4 v[138:141], v[66:67], off
	s_nop 0
	global_load_dwordx4 v[66:69], v[80:81], off offset:16
	global_load_dwordx4 v[86:89], v[80:81], off
	s_nop 0
	global_load_dwordx4 v[78:81], v[94:95], off offset:16
	s_nop 0
	global_load_dwordx4 v[94:97], v[94:95], off
.LBB0_476:
	v_pk_mul_f32 v[168:169], v[168:169], v[186:187] op_sel_hi:[1,0]
	v_pk_mul_f32 v[192:193], v[166:167], v[186:187] op_sel_hi:[1,0]
	v_pk_mul_f32 v[164:165], v[164:165], v[186:187] op_sel_hi:[1,0]
	v_pk_mul_f32 v[194:195], v[162:163], v[186:187] op_sel_hi:[1,0]
	v_pk_mul_f32 v[162:163], v[176:177], v[186:187] op_sel_hi:[1,0]
	v_pk_mul_f32 v[174:175], v[174:175], v[186:187] op_sel_hi:[1,0]
	v_pk_mul_f32 v[166:167], v[172:173], v[186:187] op_sel_hi:[1,0]
	s_and_b64 vcc, exec, s[44:45]
	v_pk_mul_f32 v[170:171], v[170:171], v[186:187] op_sel_hi:[1,0]
	s_cbranch_vccnz .LBB0_478
	v_mov_b32_e32 v176, v193
	v_mov_b32_e32 v177, v195
	v_mov_b32_e32 v172, v192
	v_mov_b32_e32 v173, v194
	v_pk_mul_f32 v[176:177], v[176:177], v[176:177]
	v_mov_b32_e32 v196, v171
	v_pk_fma_f32 v[172:173], v[172:173], v[172:173], v[176:177]
	v_mov_b32_e32 v176, v168
	v_mov_b32_e32 v177, v164
	v_pk_fma_f32 v[172:173], v[176:177], v[176:177], v[172:173]
	v_mov_b32_e32 v176, v169
	v_mov_b32_e32 v177, v165
	v_mov_b32_e32 v197, v175
	v_pk_fma_f32 v[172:173], v[176:177], v[176:177], v[172:173]
	v_mov_b32_e32 v176, v170
	v_mov_b32_e32 v177, v174
	v_pk_mul_f32 v[196:197], v[196:197], v[196:197]
	v_add_f32_e32 v172, v172, v173
	v_pk_fma_f32 v[176:177], v[176:177], v[176:177], v[196:197]
	v_mov_b32_e32 v196, v166
	v_mov_b32_e32 v197, v162
	v_pk_fma_f32 v[176:177], v[196:197], v[196:197], v[176:177]
	v_mov_b32_e32 v196, v167
	v_mov_b32_e32 v197, v163
	v_pk_fma_f32 v[176:177], v[196:197], v[196:197], v[176:177]
	v_xor_b32_e32 v173, 16, v224
	v_add_f32_e32 v172, v177, v172
	v_add_f32_e32 v172, v176, v172
	v_and_b32_e32 v176, 64, v224
	v_add_u32_e32 v176, 64, v176
	v_cmp_lt_i32_e32 vcc, v173, v176
	v_pk_mul_f32 v[168:169], v[168:169], v[16:17]
	v_pk_mul_f32 v[162:163], v[162:163], v[12:13]
	v_cndmask_b32_e32 v173, v224, v173, vcc
	v_lshlrev_b32_e32 v173, 2, v173
	ds_bpermute_b32 v173, v173, v172
	v_pk_mul_f32 v[164:165], v[164:165], v[8:9]
	s_waitcnt lgkmcnt(0)
	v_add_f32_e32 v172, v172, v173
	v_xor_b32_e32 v173, 32, v224
	v_cmp_lt_i32_e32 vcc, v173, v176
	v_pk_mul_f32 v[176:177], v[192:193], v[14:15]
	s_nop 0
	v_cndmask_b32_e32 v173, v224, v173, vcc
	v_lshlrev_b32_e32 v173, 2, v173
	ds_bpermute_b32 v173, v173, v172
	s_waitcnt lgkmcnt(0)
	v_add_f32_e32 v172, v172, v173
	v_fmamk_f32 v172, v172, 0x3c800000, v227
	v_mul_f32_e32 v173, 0x4b800000, v172
	v_cmp_gt_f32_e32 vcc, s16, v172
	s_nop 1
	v_cndmask_b32_e32 v172, v172, v173, vcc
	v_rsq_f32_e32 v172, v172
	s_nop 0
	v_mul_f32_e32 v173, 0x45800000, v172
	v_cndmask_b32_e32 v172, v172, v173, vcc
	v_mul_f32_e32 v173, 0x3e38aa3b, v172
	v_cndmask_b32_e64 v172, v172, v173, s[96:97]
	v_pk_mul_f32 v[196:197], v[168:169], v[172:173] op_sel_hi:[1,0]
	v_pk_mul_f32 v[168:169], v[174:175], v[10:11]
	v_pk_mul_f32 v[162:163], v[162:163], v[172:173] op_sel_hi:[1,0]
	v_pk_mul_f32 v[174:175], v[168:169], v[172:173] op_sel_hi:[1,0]
	v_pk_mul_f32 v[176:177], v[176:177], v[172:173] op_sel_hi:[1,0]
	s_waitcnt vmcnt(0)
	v_pk_mul_f32 v[192:193], v[138:139], v[174:175]
	v_pk_mul_f32 v[168:169], v[140:141], v[162:163]
	v_pk_fma_f32 v[192:193], v[126:127], v[176:177], v[192:193] neg_lo:[0,0,1] neg_hi:[0,0,1]
	v_pk_fma_f32 v[168:169], v[128:129], v[196:197], v[168:169] neg_lo:[0,0,1] neg_hi:[0,0,1]
	v_pk_mul_f32 v[176:177], v[138:139], v[176:177]
	v_pk_mul_f32 v[196:197], v[140:141], v[196:197]
	v_pk_fma_f32 v[174:175], v[126:127], v[174:175], v[176:177]
	v_pk_fma_f32 v[162:163], v[128:129], v[162:163], v[196:197]
	v_pk_mul_f32 v[176:177], v[194:195], v[6:7]
	v_pk_mul_f32 v[196:197], v[164:165], v[172:173] op_sel_hi:[1,0]
	v_pk_mul_f32 v[164:165], v[166:167], v[4:5]
	v_pk_mul_f32 v[166:167], v[170:171], v[2:3]
	v_pk_mul_f32 v[176:177], v[176:177], v[172:173] op_sel_hi:[1,0]
	v_pk_mul_f32 v[170:171], v[164:165], v[172:173] op_sel_hi:[1,0]
	v_pk_mul_f32 v[172:173], v[166:167], v[172:173] op_sel_hi:[1,0]
	v_pk_mul_f32 v[164:165], v[124:125], v[170:171]
	v_pk_mul_f32 v[166:167], v[122:123], v[172:173]
	v_pk_fma_f32 v[164:165], v[100:101], v[196:197], v[164:165] neg_lo:[0,0,1] neg_hi:[0,0,1]
	v_pk_fma_f32 v[194:195], v[98:99], v[176:177], v[166:167] neg_lo:[0,0,1] neg_hi:[0,0,1]
	v_pk_mul_f32 v[176:177], v[122:123], v[176:177]
	v_pk_mul_f32 v[166:167], v[124:125], v[196:197]
	s_nop 0
	v_pk_fma_f32 v[166:167], v[100:101], v[170:171], v[166:167]
	v_pk_fma_f32 v[170:171], v[98:99], v[172:173], v[176:177]
; #define LAS __attribute__((address_space(3)))
; DI unsigned cvt_pk(float lo, float hi) { unsigned r; asm("v_cvt_pk_bf16_f32 %0, %1, %2" : "=v"(r) : "v"(lo), "v"(hi)); return r; }
;   DI void operator()(LAS unsigned char* lds, f32x4 (&acc)[2][2][4][2], int pm, int pn, int wr, int wc, int fr, int fq) const {
;     ...
;       if (type < 2) {
; #pragma unroll
;         for (int m = mb; m < mb + 2; ++m)
; #pragma unroll
;           for (int n = 0; n < 2; ++n) {
;             if (aim == 0) {
;               const int tr = wr * 32 + m * 16 + fr;
;               cs[m][n] = *(const LAS f32x4*)(lds + EQ_CS + tr * EQ_CSS + (8 * fq + 4 * n) * 4);
;               sn[m][n] = *(const LAS f32x4*)(lds + EQ_CS + tr * EQ_CSS + 128 + (8 * fq + 4 * n) * 4);
;             } else {
;               const size_t o = (size_t)(s0 + ai * HALF + m * 16) * 32 + 8 * fq + 4 * n;
;               cs[m][n] = *(const f32x4*)(cosT + o); sn[m][n] = *(const f32x4*)(sinT + o);
;             }
;           }
;       }
;       EPI_FENCE;
; #pragma unroll
;       for (int m = mb; m < mb + 2; ++m) {
;         const int s = s0 + ai * HALF + m * 16;
;         f32x4 v[2][2];
; #pragma unroll
;         for (int bj = 0; bj < 2; ++bj)
; #pragma unroll
;           for (int n = 0; n < 2; ++n) v[bj][n] = acc[ai][bj][m][n] * rstd[ai][m];
;         if (type < 2) {
;           float q = 0.f;
; #pragma unroll
;           for (int bj = 0; bj < 2; ++bj)
; #pragma unroll
;             for (int n = 0; n < 2; ++n) q += v[bj][n][0] * v[bj][n][0] + v[bj][n][1] * v[bj][n][1] + v[bj][n][2] * v[bj][n][2] + v[bj][n][3] * v[bj][n][3];
;           q += __shfl_xor(q, 16); q += __shfl_xor(q, 32);
;           float rn = rsqrtf(q * (1.0f / 64.0f) + EPS);
;           if (type == 0) rn *= 0.125f * LOG2E;
; #pragma unroll
;           for (int n = 0; n < 2; ++n) {
;             const f32x4 x1 = v[0][n] * g1[n] * rn, x2 = v[1][n] * g2[n] * rn;
;             v[0][n] = x1 * cs[m][n] - x2 * sn[m][n]; v[1][n] = x2 * cs[m][n] + x1 * sn[m][n];
;           }
;         }
;         bf16_t* rp = base + (size_t)s * 64 + 8 * fq;
; #pragma unroll
;         for (int bj = 0; bj < 2; ++bj) {
;           u32x4 w; w.x = cvt_pk(v[bj][0][0], v[bj][0][1]); w.y = cvt_pk(v[bj][0][2], v[bj][0][3]); w.z = cvt_pk(v[bj][1][0], v[bj][1][1]); w.w = cvt_pk(v[bj][1][2], v[bj][1][3]);
;           *(u32x4*)(rp + bj * 32) = w;
;         }
.LBB0_478:
	v_lshlrev_b64 v[172:173], 7, v[190:191]
	v_cvt_pk_bf16_f32 v170, v170, v171
	v_cvt_pk_bf16_f32 v171, v166, v167
	v_mov_b32_e32 v166, v187
	v_lshl_add_u64 v[172:173], v[180:181], 0, v[172:173]
	v_cvt_pk_bf16_f32 v190, v192, v193
	v_cvt_pk_bf16_f32 v191, v168, v169
	v_cvt_pk_bf16_f32 v193, v164, v165
	v_cvt_pk_bf16_f32 v169, v162, v163
	v_pk_mul_f32 v[152:153], v[152:153], v[166:167] op_sel_hi:[1,0]
	v_pk_mul_f32 v[162:163], v[150:151], v[166:167] op_sel_hi:[1,0]
	v_pk_mul_f32 v[148:149], v[148:149], v[166:167] op_sel_hi:[1,0]
	v_pk_mul_f32 v[164:165], v[146:147], v[166:167] op_sel_hi:[1,0]
	v_pk_mul_f32 v[146:147], v[160:161], v[166:167] op_sel_hi:[1,0]
	v_pk_mul_f32 v[158:159], v[158:159], v[166:167] op_sel_hi:[1,0]
	v_pk_mul_f32 v[150:151], v[156:157], v[166:167] op_sel_hi:[1,0]
	s_and_b64 vcc, exec, s[44:45]
	v_pk_mul_f32 v[154:155], v[154:155], v[166:167] op_sel_hi:[1,0]
	v_cvt_pk_bf16_f32 v192, v194, v195
	global_store_dwordx4 v[172:173], v[190:193], off
	v_cvt_pk_bf16_f32 v168, v174, v175
	global_store_dwordx4 v[172:173], v[168:171], off offset:64
	s_cbranch_vccnz .LBB0_480
	v_mov_b32_e32 v160, v163
	v_mov_b32_e32 v161, v165
	v_mov_b32_e32 v156, v162
	v_mov_b32_e32 v157, v164
	v_pk_mul_f32 v[160:161], v[160:161], v[160:161]
	v_mov_b32_e32 v166, v155
	v_pk_fma_f32 v[156:157], v[156:157], v[156:157], v[160:161]
	v_mov_b32_e32 v160, v152
	v_mov_b32_e32 v161, v148
	v_pk_fma_f32 v[156:157], v[160:161], v[160:161], v[156:157]
	v_mov_b32_e32 v160, v153
	v_mov_b32_e32 v161, v149
	v_mov_b32_e32 v167, v159
	v_pk_fma_f32 v[156:157], v[160:161], v[160:161], v[156:157]
	v_mov_b32_e32 v160, v154
	v_mov_b32_e32 v161, v158
	v_pk_mul_f32 v[166:167], v[166:167], v[166:167]
	v_add_f32_e32 v156, v156, v157
	v_pk_fma_f32 v[160:161], v[160:161], v[160:161], v[166:167]
	v_mov_b32_e32 v166, v150
	v_mov_b32_e32 v167, v146
	v_pk_fma_f32 v[160:161], v[166:167], v[166:167], v[160:161]
	v_mov_b32_e32 v166, v151
	v_mov_b32_e32 v167, v147
	v_pk_fma_f32 v[160:161], v[166:167], v[166:167], v[160:161]
	v_xor_b32_e32 v157, 16, v224
	v_add_f32_e32 v156, v161, v156
	v_add_f32_e32 v156, v160, v156
	v_and_b32_e32 v160, 64, v224
	v_add_u32_e32 v160, 64, v160
	v_cmp_lt_i32_e32 vcc, v157, v160
	v_pk_mul_f32 v[152:153], v[152:153], v[16:17]
	v_pk_mul_f32 v[146:147], v[146:147], v[12:13]
	v_cndmask_b32_e32 v157, v224, v157, vcc
	v_lshlrev_b32_e32 v157, 2, v157
	ds_bpermute_b32 v157, v157, v156
	v_pk_mul_f32 v[148:149], v[148:149], v[8:9]
	s_waitcnt lgkmcnt(0)
	v_add_f32_e32 v156, v156, v157
	v_xor_b32_e32 v157, 32, v224
	v_cmp_lt_i32_e32 vcc, v157, v160
	v_pk_mul_f32 v[160:161], v[162:163], v[14:15]
	s_nop 0
	v_cndmask_b32_e32 v157, v224, v157, vcc
	v_lshlrev_b32_e32 v157, 2, v157
	ds_bpermute_b32 v157, v157, v156
	s_waitcnt lgkmcnt(0)
	v_add_f32_e32 v156, v156, v157
	v_fmamk_f32 v156, v156, 0x3c800000, v227
	v_mul_f32_e32 v157, 0x4b800000, v156
	v_cmp_gt_f32_e32 vcc, s16, v156
	s_nop 1
	v_cndmask_b32_e32 v156, v156, v157, vcc
	v_rsq_f32_e32 v156, v156
	s_nop 0
	v_mul_f32_e32 v157, 0x45800000, v156
	v_cndmask_b32_e32 v156, v156, v157, vcc
	v_mul_f32_e32 v157, 0x3e38aa3b, v156
	v_cndmask_b32_e64 v156, v156, v157, s[96:97]
	v_pk_mul_f32 v[166:167], v[152:153], v[156:157] op_sel_hi:[1,0]
	v_pk_mul_f32 v[152:153], v[158:159], v[10:11]
	v_pk_mul_f32 v[146:147], v[146:147], v[156:157] op_sel_hi:[1,0]
	v_pk_mul_f32 v[158:159], v[152:153], v[156:157] op_sel_hi:[1,0]
	v_pk_mul_f32 v[160:161], v[160:161], v[156:157] op_sel_hi:[1,0]
	s_waitcnt vmcnt(0)
	v_pk_mul_f32 v[162:163], v[94:95], v[158:159]
	v_pk_mul_f32 v[152:153], v[96:97], v[146:147]
	v_pk_fma_f32 v[162:163], v[86:87], v[160:161], v[162:163] neg_lo:[0,0,1] neg_hi:[0,0,1]
	v_pk_fma_f32 v[152:153], v[88:89], v[166:167], v[152:153] neg_lo:[0,0,1] neg_hi:[0,0,1]
	v_pk_mul_f32 v[160:161], v[94:95], v[160:161]
	v_pk_mul_f32 v[166:167], v[96:97], v[166:167]
	v_pk_fma_f32 v[158:159], v[86:87], v[158:159], v[160:161]
	v_pk_fma_f32 v[146:147], v[88:89], v[146:147], v[166:167]
	v_pk_mul_f32 v[160:161], v[164:165], v[6:7]
	v_pk_mul_f32 v[166:167], v[148:149], v[156:157] op_sel_hi:[1,0]
	v_pk_mul_f32 v[148:149], v[150:151], v[4:5]
	v_pk_mul_f32 v[150:151], v[154:155], v[2:3]
	v_pk_mul_f32 v[160:161], v[160:161], v[156:157] op_sel_hi:[1,0]
	v_pk_mul_f32 v[154:155], v[148:149], v[156:157] op_sel_hi:[1,0]
	v_pk_mul_f32 v[156:157], v[150:151], v[156:157] op_sel_hi:[1,0]
	v_pk_mul_f32 v[148:149], v[80:81], v[154:155]
	v_pk_mul_f32 v[150:151], v[78:79], v[156:157]
	v_pk_fma_f32 v[148:149], v[68:69], v[166:167], v[148:149] neg_lo:[0,0,1] neg_hi:[0,0,1]
	v_pk_fma_f32 v[164:165], v[66:67], v[160:161], v[150:151] neg_lo:[0,0,1] neg_hi:[0,0,1]
	v_pk_mul_f32 v[160:161], v[78:79], v[160:161]
	v_pk_mul_f32 v[150:151], v[80:81], v[166:167]
	s_nop 0
	v_pk_fma_f32 v[150:151], v[68:69], v[154:155], v[150:151]
	v_pk_fma_f32 v[154:155], v[66:67], v[156:157], v[160:161]
.LBB0_480:
	v_lshlrev_b64 v[156:157], 7, v[188:189]
	v_lshl_add_u64 v[156:157], v[180:181], 0, v[156:157]
	v_cvt_pk_bf16_f32 v160, v162, v163
	v_cvt_pk_bf16_f32 v161, v152, v153
	v_cvt_pk_bf16_f32 v162, v164, v165
	v_cvt_pk_bf16_f32 v163, v148, v149
	global_store_dwordx4 v[156:157], v[160:163], off
	v_cvt_pk_bf16_f32 v152, v158, v159
	v_cvt_pk_bf16_f32 v153, v146, v147
	v_cvt_pk_bf16_f32 v154, v154, v155
	v_cvt_pk_bf16_f32 v155, v150, v151
	global_store_dwordx4 v[156:157], v[152:155], off offset:64
	v_add_u32_e32 v146, 0x80, v182
	s_and_b64 vcc, exec, s[44:45]
	v_ashrrev_i32_e32 v147, 31, v146
	s_cbranch_vccnz .LBB0_482
	v_lshlrev_b64 v[70:71], 7, v[146:147]
	v_readlane_b32 s18, v254, 8
	v_readlane_b32 s20, v254, 10
	v_or_b32_e32 v70, v70, v0
	v_readlane_b32 s19, v254, 9
	v_readlane_b32 s21, v254, 11
	s_mov_b64 s[28:29], 0x4800
	v_lshl_add_u64 v[72:73], s[18:19], 0, v[70:71]
	v_lshl_add_u64 v[70:71], s[20:21], 0, v[70:71]
	global_load_dwordx4 v[114:117], v[72:73], off offset:16
	global_load_dwordx4 v[134:137], v[72:73], off
	global_load_dwordx4 v[130:133], v[70:71], off offset:16
	global_load_dwordx4 v[142:145], v[70:71], off
	v_lshlrev_b64 v[70:71], 7, v[182:183]
	v_or_b32_e32 v70, v70, v0
	v_lshl_add_u64 v[74:75], v[70:71], 0, s[28:29]
	v_lshl_add_u64 v[76:77], s[18:19], 0, v[74:75]
	v_lshl_add_u64 v[90:91], s[20:21], 0, v[74:75]
	global_load_dwordx4 v[70:73], v[76:77], off offset:16
	global_load_dwordx4 v[82:85], v[76:77], off
	s_nop 0
	global_load_dwordx4 v[74:77], v[90:91], off offset:16
	s_nop 0
	global_load_dwordx4 v[90:93], v[90:91], off
;   DI void operator()(LAS unsigned char* lds, f32x4 (&acc)[2][2][4][2], int pm, int pn, int wr, int wc, int fr, int fq) const {
;     ...
;       for (int m = mb; m < mb + 2; ++m) {
;         const int s = s0 + ai * HALF + m * 16;
;         f32x4 v[2][2];
; #pragma unroll
;         for (int bj = 0; bj < 2; ++bj)
; #pragma unroll
;           for (int n = 0; n < 2; ++n) v[bj][n] = acc[ai][bj][m][n] * rstd[ai][m];
;         if (type < 2) {
;           float q = 0.f;
; #pragma unroll
;           for (int bj = 0; bj < 2; ++bj)
; #pragma unroll
;             for (int n = 0; n < 2; ++n) q += v[bj][n][0] * v[bj][n][0] + v[bj][n][1] * v[bj][n][1] + v[bj][n][2] * v[bj][n][2] + v[bj][n][3] * v[bj][n][3];
;           q += __shfl_xor(q, 16); q += __shfl_xor(q, 32);
;           float rn = rsqrtf(q * (1.0f / 64.0f) + EPS);
;           if (type == 0) rn *= 0.125f * LOG2E;
; #pragma unroll
;           for (int n = 0; n < 2; ++n) {
;             const f32x4 x1 = v[0][n] * g1[n] * rn, x2 = v[1][n] * g2[n] * rn;
;             v[0][n] = x1 * cs[m][n] - x2 * sn[m][n]; v[1][n] = x2 * cs[m][n] + x1 * sn[m][n];
;           }
;         }
.LBB0_482:
	v_pk_mul_f32 v[112:113], v[112:113], v[184:185] op_sel_hi:[1,0]
	v_pk_mul_f32 v[110:111], v[110:111], v[184:185] op_sel_hi:[1,0]
	v_pk_mul_f32 v[108:109], v[108:109], v[184:185] op_sel_hi:[1,0]
	v_pk_mul_f32 v[148:149], v[106:107], v[184:185] op_sel_hi:[1,0]
	v_pk_mul_f32 v[106:107], v[120:121], v[184:185] op_sel_hi:[1,0]
	v_pk_mul_f32 v[118:119], v[118:119], v[184:185] op_sel_hi:[1,0]
	v_pk_mul_f32 v[104:105], v[104:105], v[184:185] op_sel_hi:[1,0]
	s_and_b64 vcc, exec, s[44:45]
	v_pk_mul_f32 v[102:103], v[102:103], v[184:185] op_sel_hi:[1,0]
	s_cbranch_vccnz .LBB0_484
	v_mov_b32_e32 v150, v111
	v_mov_b32_e32 v151, v149
	v_mov_b32_e32 v120, v110
	v_mov_b32_e32 v121, v148
	v_pk_mul_f32 v[150:151], v[150:151], v[150:151]
	v_mov_b32_e32 v152, v103
	v_pk_fma_f32 v[120:121], v[120:121], v[120:121], v[150:151]
	v_mov_b32_e32 v150, v112
	v_mov_b32_e32 v151, v108
	v_pk_fma_f32 v[120:121], v[150:151], v[150:151], v[120:121]
	v_mov_b32_e32 v150, v113
	v_mov_b32_e32 v151, v109
	v_mov_b32_e32 v153, v119
	v_pk_fma_f32 v[120:121], v[150:151], v[150:151], v[120:121]
	v_mov_b32_e32 v150, v102
	v_mov_b32_e32 v151, v118
	v_pk_mul_f32 v[152:153], v[152:153], v[152:153]
	v_add_f32_e32 v120, v120, v121
	v_pk_fma_f32 v[150:151], v[150:151], v[150:151], v[152:153]
	v_mov_b32_e32 v152, v104
	v_mov_b32_e32 v153, v106
	v_pk_fma_f32 v[150:151], v[152:153], v[152:153], v[150:151]
	v_mov_b32_e32 v152, v105
	v_mov_b32_e32 v153, v107
	v_pk_fma_f32 v[150:151], v[152:153], v[152:153], v[150:151]
	v_xor_b32_e32 v121, 16, v224
	v_add_f32_e32 v120, v151, v120
	v_add_f32_e32 v120, v150, v120
	v_and_b32_e32 v150, 64, v224
	v_add_u32_e32 v150, 64, v150
	v_cmp_lt_i32_e32 vcc, v121, v150
	v_pk_mul_f32 v[110:111], v[110:111], v[14:15]
	v_pk_mul_f32 v[112:113], v[112:113], v[16:17]
	v_cndmask_b32_e32 v121, v224, v121, vcc
	v_lshlrev_b32_e32 v121, 2, v121
	ds_bpermute_b32 v121, v121, v120
	v_pk_mul_f32 v[106:107], v[106:107], v[12:13]
	v_pk_mul_f32 v[102:103], v[102:103], v[2:3]
	v_pk_mul_f32 v[108:109], v[108:109], v[8:9]
	v_pk_mul_f32 v[104:105], v[104:105], v[4:5]
	s_waitcnt lgkmcnt(0)
	v_add_f32_e32 v120, v120, v121
	v_xor_b32_e32 v121, 32, v224
	v_cmp_lt_i32_e32 vcc, v121, v150
	s_nop 1
	v_cndmask_b32_e32 v121, v224, v121, vcc
	v_lshlrev_b32_e32 v121, 2, v121
	ds_bpermute_b32 v121, v121, v120
	s_waitcnt lgkmcnt(0)
	v_add_f32_e32 v120, v120, v121
	v_fmamk_f32 v120, v120, 0x3c800000, v227
	v_mul_f32_e32 v121, 0x4b800000, v120
	v_cmp_gt_f32_e32 vcc, s16, v120
	s_nop 1
	v_cndmask_b32_e32 v120, v120, v121, vcc
	v_rsq_f32_e32 v120, v120
	s_nop 0
	v_mul_f32_e32 v121, 0x45800000, v120
	v_cndmask_b32_e32 v120, v120, v121, vcc
	v_mul_f32_e32 v121, 0x3e38aa3b, v120
	v_cndmask_b32_e64 v120, v120, v121, s[96:97]
	v_pk_mul_f32 v[150:151], v[110:111], v[120:121] op_sel_hi:[1,0]
	v_pk_mul_f32 v[110:111], v[118:119], v[10:11]
	v_pk_mul_f32 v[152:153], v[112:113], v[120:121] op_sel_hi:[1,0]
	v_pk_mul_f32 v[118:119], v[110:111], v[120:121] op_sel_hi:[1,0]
	v_pk_mul_f32 v[106:107], v[106:107], v[120:121] op_sel_hi:[1,0]
	s_waitcnt vmcnt(0)
	v_pk_mul_f32 v[110:111], v[142:143], v[118:119]
	v_pk_mul_f32 v[142:143], v[142:143], v[150:151]
	v_pk_mul_f32 v[112:113], v[144:145], v[106:107]
	v_pk_fma_f32 v[110:111], v[134:135], v[150:151], v[110:111] neg_lo:[0,0,1] neg_hi:[0,0,1]
	v_pk_mul_f32 v[144:145], v[144:145], v[152:153]
	v_pk_fma_f32 v[118:119], v[134:135], v[118:119], v[142:143]
	v_pk_mul_f32 v[134:135], v[148:149], v[6:7]
	v_pk_mul_f32 v[102:103], v[102:103], v[120:121] op_sel_hi:[1,0]
	v_pk_fma_f32 v[112:113], v[136:137], v[152:153], v[112:113] neg_lo:[0,0,1] neg_hi:[0,0,1]
	v_pk_fma_f32 v[106:107], v[136:137], v[106:107], v[144:145]
	v_pk_mul_f32 v[134:135], v[134:135], v[120:121] op_sel_hi:[1,0]
	v_pk_mul_f32 v[136:137], v[108:109], v[120:121] op_sel_hi:[1,0]
	v_pk_mul_f32 v[104:105], v[104:105], v[120:121] op_sel_hi:[1,0]
	v_pk_mul_f32 v[120:121], v[130:131], v[102:103]
	v_pk_mul_f32 v[108:109], v[132:133], v[104:105]
	v_pk_fma_f32 v[148:149], v[114:115], v[134:135], v[120:121] neg_lo:[0,0,1] neg_hi:[0,0,1]
	v_pk_mul_f32 v[120:121], v[130:131], v[134:135]
	v_pk_mul_f32 v[130:131], v[132:133], v[136:137]
	v_pk_fma_f32 v[108:109], v[116:117], v[136:137], v[108:109] neg_lo:[0,0,1] neg_hi:[0,0,1]
	v_pk_fma_f32 v[104:105], v[116:117], v[104:105], v[130:131]
	v_pk_fma_f32 v[102:103], v[114:115], v[102:103], v[120:121]
; #define LAS __attribute__((address_space(3)))
; DI unsigned cvt_pk(float lo, float hi) { unsigned r; asm("v_cvt_pk_bf16_f32 %0, %1, %2" : "=v"(r) : "v"(lo), "v"(hi)); return r; }
;   DI void operator()(LAS unsigned char* lds, f32x4 (&acc)[2][2][4][2], int pm, int pn, int wr, int wc, int fr, int fq) const {
;     ...
;       if (type < 2) {
; #pragma unroll
;         for (int m = mb; m < mb + 2; ++m)
; #pragma unroll
;           for (int n = 0; n < 2; ++n) {
;             if (aim == 0) {
;               const int tr = wr * 32 + m * 16 + fr;
;               cs[m][n] = *(const LAS f32x4*)(lds + EQ_CS + tr * EQ_CSS + (8 * fq + 4 * n) * 4);
;               sn[m][n] = *(const LAS f32x4*)(lds + EQ_CS + tr * EQ_CSS + 128 + (8 * fq + 4 * n) * 4);
;             } else {
;               const size_t o = (size_t)(s0 + ai * HALF + m * 16) * 32 + 8 * fq + 4 * n;
;               cs[m][n] = *(const f32x4*)(cosT + o); sn[m][n] = *(const f32x4*)(sinT + o);
;             }
;           }
;       }
;       EPI_FENCE;
; #pragma unroll
;       for (int m = mb; m < mb + 2; ++m) {
;         const int s = s0 + ai * HALF + m * 16;
;         f32x4 v[2][2];
; #pragma unroll
;         for (int bj = 0; bj < 2; ++bj)
; #pragma unroll
;           for (int n = 0; n < 2; ++n) v[bj][n] = acc[ai][bj][m][n] * rstd[ai][m];
;         if (type < 2) {
;           float q = 0.f;
; #pragma unroll
;           for (int bj = 0; bj < 2; ++bj)
; #pragma unroll
;             for (int n = 0; n < 2; ++n) q += v[bj][n][0] * v[bj][n][0] + v[bj][n][1] * v[bj][n][1] + v[bj][n][2] * v[bj][n][2] + v[bj][n][3] * v[bj][n][3];
;           q += __shfl_xor(q, 16); q += __shfl_xor(q, 32);
;           float rn = rsqrtf(q * (1.0f / 64.0f) + EPS);
;           if (type == 0) rn *= 0.125f * LOG2E;
; #pragma unroll
;           for (int n = 0; n < 2; ++n) {
;             const f32x4 x1 = v[0][n] * g1[n] * rn, x2 = v[1][n] * g2[n] * rn;
;             v[0][n] = x1 * cs[m][n] - x2 * sn[m][n]; v[1][n] = x2 * cs[m][n] + x1 * sn[m][n];
;           }
;         }
;         bf16_t* rp = base + (size_t)s * 64 + 8 * fq;
; #pragma unroll
;         for (int bj = 0; bj < 2; ++bj) {
;           u32x4 w; w.x = cvt_pk(v[bj][0][0], v[bj][0][1]); w.y = cvt_pk(v[bj][0][2], v[bj][0][3]); w.z = cvt_pk(v[bj][1][0], v[bj][1][1]); w.w = cvt_pk(v[bj][1][2], v[bj][1][3]);
;           *(u32x4*)(rp + bj * 32) = w;
;         }
.LBB0_484:
	s_waitcnt vmcnt(0)
	v_lshlrev_b64 v[114:115], 7, v[146:147]
	v_lshl_add_u64 v[114:115], v[180:181], 0, v[114:115]
	v_cvt_pk_bf16_f32 v110, v110, v111
	v_cvt_pk_bf16_f32 v111, v112, v113
	v_cvt_pk_bf16_f32 v113, v108, v109
	v_cvt_pk_bf16_f32 v109, v106, v107
	v_mov_b32_e32 v106, v185
	v_cvt_pk_bf16_f32 v112, v148, v149
	global_store_dwordx4 v[114:115], v[110:113], off
	v_pk_mul_f32 v[60:61], v[60:61], v[106:107] op_sel_hi:[1,0]
	v_pk_mul_f32 v[52:53], v[52:53], v[106:107] op_sel_hi:[1,0]
	v_cvt_pk_bf16_f32 v110, v102, v103
	v_cvt_pk_bf16_f32 v111, v104, v105
	v_pk_mul_f32 v[102:103], v[58:59], v[106:107] op_sel_hi:[1,0]
	v_pk_mul_f32 v[58:59], v[56:57], v[106:107] op_sel_hi:[1,0]
	v_pk_mul_f32 v[104:105], v[54:55], v[106:107] op_sel_hi:[1,0]
	v_pk_mul_f32 v[54:55], v[64:65], v[106:107] op_sel_hi:[1,0]
	v_pk_mul_f32 v[56:57], v[62:63], v[106:107] op_sel_hi:[1,0]
	s_and_b64 vcc, exec, s[44:45]
	v_pk_mul_f32 v[50:51], v[50:51], v[106:107] op_sel_hi:[1,0]
	v_cvt_pk_bf16_f32 v108, v118, v119
	global_store_dwordx4 v[114:115], v[108:111], off offset:64
	s_cbranch_vccnz .LBB0_486
	v_mov_b32_e32 v64, v103
	v_mov_b32_e32 v65, v105
	v_mov_b32_e32 v62, v102
	v_mov_b32_e32 v63, v104
	v_pk_mul_f32 v[64:65], v[64:65], v[64:65]
	v_mov_b32_e32 v106, v51
	v_pk_fma_f32 v[62:63], v[62:63], v[62:63], v[64:65]
	v_mov_b32_e32 v64, v60
	v_mov_b32_e32 v65, v58
	v_pk_fma_f32 v[62:63], v[64:65], v[64:65], v[62:63]
	v_mov_b32_e32 v64, v61
	v_mov_b32_e32 v65, v59
	v_mov_b32_e32 v107, v57
	v_pk_fma_f32 v[62:63], v[64:65], v[64:65], v[62:63]
	v_mov_b32_e32 v64, v50
	v_mov_b32_e32 v65, v56
	v_pk_mul_f32 v[106:107], v[106:107], v[106:107]
	v_add_f32_e32 v62, v62, v63
	v_pk_fma_f32 v[64:65], v[64:65], v[64:65], v[106:107]
	v_mov_b32_e32 v106, v52
	v_mov_b32_e32 v107, v54
	v_pk_fma_f32 v[64:65], v[106:107], v[106:107], v[64:65]
	v_mov_b32_e32 v106, v53
	v_mov_b32_e32 v107, v55
	v_pk_fma_f32 v[64:65], v[106:107], v[106:107], v[64:65]
	v_xor_b32_e32 v63, 16, v224
	v_add_f32_e32 v62, v65, v62
	v_add_f32_e32 v62, v64, v62
	v_and_b32_e32 v64, 64, v224
	v_add_u32_e32 v64, 64, v64
	v_cmp_lt_i32_e32 vcc, v63, v64
	v_pk_mul_f32 v[56:57], v[56:57], v[10:11]
	v_pk_mul_f32 v[50:51], v[50:51], v[2:3]
	v_cndmask_b32_e32 v63, v224, v63, vcc
	v_lshlrev_b32_e32 v63, 2, v63
	ds_bpermute_b32 v63, v63, v62
	v_pk_mul_f32 v[60:61], v[60:61], v[16:17]
	v_pk_mul_f32 v[54:55], v[54:55], v[12:13]
	v_pk_mul_f32 v[58:59], v[58:59], v[8:9]
	v_pk_mul_f32 v[52:53], v[52:53], v[4:5]
	s_waitcnt lgkmcnt(0)
	v_add_f32_e32 v62, v62, v63
	v_xor_b32_e32 v63, 32, v224
	v_cmp_lt_i32_e32 vcc, v63, v64
	v_pk_mul_f32 v[64:65], v[102:103], v[14:15]
	s_nop 0
	v_cndmask_b32_e32 v63, v224, v63, vcc
	v_lshlrev_b32_e32 v63, 2, v63
	ds_bpermute_b32 v63, v63, v62
	s_waitcnt lgkmcnt(0)
	v_add_f32_e32 v62, v62, v63
	v_fmamk_f32 v62, v62, 0x3c800000, v227
	v_mul_f32_e32 v63, 0x4b800000, v62
	v_cmp_gt_f32_e32 vcc, s16, v62
	s_nop 1
	v_cndmask_b32_e32 v62, v62, v63, vcc
	v_rsq_f32_e32 v62, v62
	s_nop 0
	v_mul_f32_e32 v63, 0x45800000, v62
	v_cndmask_b32_e32 v62, v62, v63, vcc
	v_mul_f32_e32 v63, 0x3e38aa3b, v62
	v_cndmask_b32_e64 v62, v62, v63, s[96:97]
	v_pk_mul_f32 v[56:57], v[56:57], v[62:63] op_sel_hi:[1,0]
	v_pk_mul_f32 v[64:65], v[64:65], v[62:63] op_sel_hi:[1,0]
	v_pk_mul_f32 v[102:103], v[90:91], v[56:57]
	v_pk_mul_f32 v[50:51], v[50:51], v[62:63] op_sel_hi:[1,0]
	v_pk_fma_f32 v[102:103], v[82:83], v[64:65], v[102:103] neg_lo:[0,0,1] neg_hi:[0,0,1]
	v_pk_mul_f32 v[64:65], v[90:91], v[64:65]
	v_pk_mul_f32 v[106:107], v[60:61], v[62:63] op_sel_hi:[1,0]
	v_pk_fma_f32 v[56:57], v[82:83], v[56:57], v[64:65]
	v_pk_mul_f32 v[64:65], v[104:105], v[6:7]
	v_pk_mul_f32 v[54:55], v[54:55], v[62:63] op_sel_hi:[1,0]
	v_pk_mul_f32 v[64:65], v[64:65], v[62:63] op_sel_hi:[1,0]
	v_pk_mul_f32 v[82:83], v[58:59], v[62:63] op_sel_hi:[1,0]
	v_pk_mul_f32 v[52:53], v[52:53], v[62:63] op_sel_hi:[1,0]
	v_pk_mul_f32 v[62:63], v[74:75], v[50:51]
	v_pk_mul_f32 v[60:61], v[92:93], v[54:55]
	v_pk_mul_f32 v[90:91], v[92:93], v[106:107]
	v_pk_mul_f32 v[58:59], v[76:77], v[52:53]
	v_pk_fma_f32 v[104:105], v[70:71], v[64:65], v[62:63] neg_lo:[0,0,1] neg_hi:[0,0,1]
	v_pk_mul_f32 v[62:63], v[74:75], v[64:65]
	v_pk_mul_f32 v[64:65], v[76:77], v[82:83]
	v_pk_fma_f32 v[60:61], v[84:85], v[106:107], v[60:61] neg_lo:[0,0,1] neg_hi:[0,0,1]
	v_pk_fma_f32 v[54:55], v[84:85], v[54:55], v[90:91]
	v_pk_fma_f32 v[58:59], v[72:73], v[82:83], v[58:59] neg_lo:[0,0,1] neg_hi:[0,0,1]
	v_pk_fma_f32 v[52:53], v[72:73], v[52:53], v[64:65]
	v_pk_fma_f32 v[50:51], v[70:71], v[50:51], v[62:63]
.LBB0_486:
	v_lshlrev_b64 v[62:63], 7, v[182:183]
	v_lshl_add_u64 v[64:65], v[180:181], 0, v[62:63]
	s_mov_b64 s[18:19], 0x4800
	v_lshl_add_u64 v[74:75], v[64:65], 0, s[18:19]
	s_movk_i32 s18, 0x4000
	v_cvt_pk_bf16_f32 v73, v58, v59
	v_add_co_u32_e32 v58, vcc, s18, v64
	v_cvt_pk_bf16_f32 v70, v102, v103
	v_cvt_pk_bf16_f32 v71, v60, v61
	v_cvt_pk_bf16_f32 v72, v104, v105
	v_cvt_pk_bf16_f32 v56, v56, v57
	s_nop 1
	v_addc_co_u32_e32 v59, vcc, 0, v65, vcc
	global_store_dwordx4 v[58:59], v[70:73], off offset:2048
	v_cvt_pk_bf16_f32 v57, v54, v55
	v_cvt_pk_bf16_f32 v58, v50, v51
	v_cvt_pk_bf16_f32 v59, v52, v53
	global_store_dwordx4 v[74:75], v[56:59], off offset:64
	v_add_u32_e32 v50, 0xa0, v182
	s_and_b64 vcc, exec, s[44:45]
	v_ashrrev_i32_e32 v51, 31, v50
	s_cbranch_vccnz .LBB0_488
	v_lshlrev_b64 v[52:53], 7, v[50:51]
	v_readlane_b32 s18, v254, 8
	v_readlane_b32 s20, v254, 10
	v_or_b32_e32 v52, v52, v0
	v_readlane_b32 s19, v254, 9
	v_readlane_b32 s21, v254, 11
	v_or_b32_e32 v62, v62, v0
	v_lshl_add_u64 v[54:55], s[18:19], 0, v[52:53]
	v_lshl_add_u64 v[52:53], s[20:21], 0, v[52:53]
	s_mov_b64 s[28:29], 0x5800
	global_load_dwordx4 v[98:101], v[54:55], off offset:16
	global_load_dwordx4 v[126:129], v[54:55], off
	global_load_dwordx4 v[122:125], v[52:53], off offset:16
	global_load_dwordx4 v[138:141], v[52:53], off
	v_lshl_add_u64 v[52:53], v[62:63], 0, s[28:29]
	v_lshl_add_u64 v[54:55], s[18:19], 0, v[52:53]
	v_lshl_add_u64 v[52:53], s[20:21], 0, v[52:53]
	global_load_dwordx4 v[66:69], v[54:55], off offset:16
	global_load_dwordx4 v[86:89], v[54:55], off
	global_load_dwordx4 v[78:81], v[52:53], off offset:16
	global_load_dwordx4 v[94:97], v[52:53], off
;   DI void operator()(LAS unsigned char* lds, f32x4 (&acc)[2][2][4][2], int pm, int pn, int wr, int wc, int fr, int fq) const {
;     ...
;       for (int m = mb; m < mb + 2; ++m) {
;         const int s = s0 + ai * HALF + m * 16;
;         f32x4 v[2][2];
; #pragma unroll
;         for (int bj = 0; bj < 2; ++bj)
; #pragma unroll
;           for (int n = 0; n < 2; ++n) v[bj][n] = acc[ai][bj][m][n] * rstd[ai][m];
;         if (type < 2) {
;           float q = 0.f;
; #pragma unroll
;           for (int bj = 0; bj < 2; ++bj)
; #pragma unroll
;             for (int n = 0; n < 2; ++n) q += v[bj][n][0] * v[bj][n][0] + v[bj][n][1] * v[bj][n][1] + v[bj][n][2] * v[bj][n][2] + v[bj][n][3] * v[bj][n][3];
;           q += __shfl_xor(q, 16); q += __shfl_xor(q, 32);
;           float rn = rsqrtf(q * (1.0f / 64.0f) + EPS);
;           if (type == 0) rn *= 0.125f * LOG2E;
; #pragma unroll
;           for (int n = 0; n < 2; ++n) {
;             const f32x4 x1 = v[0][n] * g1[n] * rn, x2 = v[1][n] * g2[n] * rn;
;             v[0][n] = x1 * cs[m][n] - x2 * sn[m][n]; v[1][n] = x2 * cs[m][n] + x1 * sn[m][n];
;           }
;         }
.LBB0_488:
	v_pk_mul_f32 v[44:45], v[44:45], v[178:179] op_sel_hi:[1,0]
	v_pk_mul_f32 v[42:43], v[42:43], v[178:179] op_sel_hi:[1,0]
	v_pk_mul_f32 v[40:41], v[40:41], v[178:179] op_sel_hi:[1,0]
	v_pk_mul_f32 v[52:53], v[38:39], v[178:179] op_sel_hi:[1,0]
	v_pk_mul_f32 v[38:39], v[48:49], v[178:179] op_sel_hi:[1,0]
	v_pk_mul_f32 v[46:47], v[46:47], v[178:179] op_sel_hi:[1,0]
	v_pk_mul_f32 v[36:37], v[36:37], v[178:179] op_sel_hi:[1,0]
	s_and_b64 vcc, exec, s[44:45]
	v_pk_mul_f32 v[34:35], v[34:35], v[178:179] op_sel_hi:[1,0]
	s_cbranch_vccnz .LBB0_490
	v_mov_b32_e32 v54, v43
	v_mov_b32_e32 v55, v53
	v_mov_b32_e32 v48, v42
	v_mov_b32_e32 v49, v52
	v_pk_mul_f32 v[54:55], v[54:55], v[54:55]
	v_mov_b32_e32 v56, v35
	v_pk_fma_f32 v[48:49], v[48:49], v[48:49], v[54:55]
	v_mov_b32_e32 v54, v44
	v_mov_b32_e32 v55, v40
	v_pk_fma_f32 v[48:49], v[54:55], v[54:55], v[48:49]
	v_mov_b32_e32 v54, v45
	v_mov_b32_e32 v55, v41
	v_mov_b32_e32 v57, v47
	v_pk_fma_f32 v[48:49], v[54:55], v[54:55], v[48:49]
	v_mov_b32_e32 v54, v34
	v_mov_b32_e32 v55, v46
	v_pk_mul_f32 v[56:57], v[56:57], v[56:57]
	v_add_f32_e32 v0, v48, v49
	v_pk_fma_f32 v[54:55], v[54:55], v[54:55], v[56:57]
	v_mov_b32_e32 v56, v36
	v_mov_b32_e32 v57, v38
	v_and_b32_e32 v49, 64, v224
	v_pk_fma_f32 v[54:55], v[56:57], v[56:57], v[54:55]
	v_mov_b32_e32 v56, v37
	v_mov_b32_e32 v57, v39
	v_xor_b32_e32 v48, 16, v224
	v_add_u32_e32 v49, 64, v49
	v_pk_fma_f32 v[54:55], v[56:57], v[56:57], v[54:55]
	v_cmp_lt_i32_e32 vcc, v48, v49
	v_add_f32_e32 v0, v55, v0
	v_add_f32_e32 v0, v54, v0
	v_cndmask_b32_e32 v48, v224, v48, vcc
	v_lshlrev_b32_e32 v48, 2, v48
	ds_bpermute_b32 v48, v48, v0
	v_pk_mul_f32 v[42:43], v[42:43], v[14:15]
	v_pk_mul_f32 v[38:39], v[38:39], v[12:13]
	v_pk_mul_f32 v[44:45], v[44:45], v[16:17]
	v_pk_mul_f32 v[36:37], v[36:37], v[4:5]
	s_waitcnt lgkmcnt(0)
	v_add_f32_e32 v0, v0, v48
	v_xor_b32_e32 v48, 32, v224
	v_cmp_lt_i32_e32 vcc, v48, v49
	v_pk_mul_f32 v[34:35], v[34:35], v[2:3]
	v_pk_mul_f32 v[40:41], v[40:41], v[8:9]
	v_cndmask_b32_e32 v48, v224, v48, vcc
	v_lshlrev_b32_e32 v48, 2, v48
	ds_bpermute_b32 v48, v48, v0
	s_waitcnt lgkmcnt(0)
	v_add_f32_e32 v0, v0, v48
	v_fmamk_f32 v0, v0, 0x3c800000, v227
	v_mul_f32_e32 v48, 0x4b800000, v0
	v_cmp_gt_f32_e32 vcc, s16, v0
	s_nop 1
	v_cndmask_b32_e32 v0, v0, v48, vcc
	v_rsq_f32_e32 v0, v0
	s_nop 0
	v_mul_f32_e32 v48, 0x45800000, v0
	v_cndmask_b32_e32 v0, v0, v48, vcc
	v_mul_f32_e32 v48, 0x3e38aa3b, v0
	v_cndmask_b32_e64 v0, v0, v48, s[96:97]
	v_pk_mul_f32 v[48:49], v[42:43], v[0:1] op_sel_hi:[1,0]
	v_pk_mul_f32 v[42:43], v[46:47], v[10:11]
	v_pk_mul_f32 v[38:39], v[38:39], v[0:1] op_sel_hi:[1,0]
	v_pk_mul_f32 v[46:47], v[42:43], v[0:1] op_sel_hi:[1,0]
	v_pk_mul_f32 v[54:55], v[44:45], v[0:1] op_sel_hi:[1,0]
	s_waitcnt vmcnt(4)
	v_pk_mul_f32 v[42:43], v[138:139], v[46:47]
	v_pk_mul_f32 v[44:45], v[140:141], v[38:39]
	v_pk_fma_f32 v[42:43], v[126:127], v[48:49], v[42:43] neg_lo:[0,0,1] neg_hi:[0,0,1]
	v_pk_mul_f32 v[48:49], v[138:139], v[48:49]
	v_pk_fma_f32 v[44:45], v[128:129], v[54:55], v[44:45] neg_lo:[0,0,1] neg_hi:[0,0,1]
	v_pk_mul_f32 v[54:55], v[140:141], v[54:55]
	v_pk_fma_f32 v[46:47], v[126:127], v[46:47], v[48:49]
	v_pk_mul_f32 v[48:49], v[52:53], v[6:7]
	v_pk_mul_f32 v[36:37], v[36:37], v[0:1] op_sel_hi:[1,0]
	v_pk_mul_f32 v[34:35], v[34:35], v[0:1] op_sel_hi:[1,0]
	v_pk_fma_f32 v[38:39], v[128:129], v[38:39], v[54:55]
	v_pk_mul_f32 v[48:49], v[48:49], v[0:1] op_sel_hi:[1,0]
	v_pk_mul_f32 v[54:55], v[40:41], v[0:1] op_sel_hi:[1,0]
	v_pk_mul_f32 v[52:53], v[122:123], v[34:35]
	v_pk_mul_f32 v[40:41], v[124:125], v[36:37]
	v_pk_fma_f32 v[52:53], v[98:99], v[48:49], v[52:53] neg_lo:[0,0,1] neg_hi:[0,0,1]
	v_pk_fma_f32 v[40:41], v[100:101], v[54:55], v[40:41] neg_lo:[0,0,1] neg_hi:[0,0,1]
	v_pk_mul_f32 v[48:49], v[122:123], v[48:49]
	v_pk_mul_f32 v[54:55], v[124:125], v[54:55]
	v_pk_fma_f32 v[34:35], v[98:99], v[34:35], v[48:49]
	v_pk_fma_f32 v[36:37], v[100:101], v[36:37], v[54:55]
; DI unsigned cvt_pk(float lo, float hi) { unsigned r; asm("v_cvt_pk_bf16_f32 %0, %1, %2" : "=v"(r) : "v"(lo), "v"(hi)); return r; }
;   DI void operator()(LAS unsigned char* lds, f32x4 (&acc)[2][2][4][2], int pm, int pn, int wr, int wc, int fr, int fq) const {
;     ...
;       for (int m = mb; m < mb + 2; ++m) {
;         const int s = s0 + ai * HALF + m * 16;
;         f32x4 v[2][2];
; #pragma unroll
;         for (int bj = 0; bj < 2; ++bj)
; #pragma unroll
;           for (int n = 0; n < 2; ++n) v[bj][n] = acc[ai][bj][m][n] * rstd[ai][m];
;         if (type < 2) {
;           float q = 0.f;
; #pragma unroll
;           for (int bj = 0; bj < 2; ++bj)
; #pragma unroll
;             for (int n = 0; n < 2; ++n) q += v[bj][n][0] * v[bj][n][0] + v[bj][n][1] * v[bj][n][1] + v[bj][n][2] * v[bj][n][2] + v[bj][n][3] * v[bj][n][3];
;           q += __shfl_xor(q, 16); q += __shfl_xor(q, 32);
;           float rn = rsqrtf(q * (1.0f / 64.0f) + EPS);
;           if (type == 0) rn *= 0.125f * LOG2E;
; #pragma unroll
;           for (int n = 0; n < 2; ++n) {
;             const f32x4 x1 = v[0][n] * g1[n] * rn, x2 = v[1][n] * g2[n] * rn;
;             v[0][n] = x1 * cs[m][n] - x2 * sn[m][n]; v[1][n] = x2 * cs[m][n] + x1 * sn[m][n];
;           }
;         }
;         bf16_t* rp = base + (size_t)s * 64 + 8 * fq;
; #pragma unroll
;         for (int bj = 0; bj < 2; ++bj) {
;           u32x4 w; w.x = cvt_pk(v[bj][0][0], v[bj][0][1]); w.y = cvt_pk(v[bj][0][2], v[bj][0][3]); w.z = cvt_pk(v[bj][1][0], v[bj][1][1]); w.w = cvt_pk(v[bj][1][2], v[bj][1][3]);
;           *(u32x4*)(rp + bj * 32) = w;
;         }
.LBB0_490:
	v_lshlrev_b64 v[48:49], 7, v[50:51]
	v_lshl_add_u64 v[48:49], v[180:181], 0, v[48:49]
	v_cvt_pk_bf16_f32 v42, v42, v43
	v_cvt_pk_bf16_f32 v43, v44, v45
	v_mov_b32_e32 v0, v179
	v_cvt_pk_bf16_f32 v44, v52, v53
	v_cvt_pk_bf16_f32 v45, v40, v41
	global_store_dwordx4 v[48:49], v[42:45], off
	v_pk_mul_f32 v[28:29], v[28:29], v[0:1] op_sel_hi:[1,0]
	v_pk_mul_f32 v[20:21], v[20:21], v[0:1] op_sel_hi:[1,0]
	v_cvt_pk_bf16_f32 v42, v34, v35
	v_cvt_pk_bf16_f32 v43, v36, v37
	v_pk_mul_f32 v[34:35], v[26:27], v[0:1] op_sel_hi:[1,0]
	v_pk_mul_f32 v[26:27], v[24:25], v[0:1] op_sel_hi:[1,0]
	v_pk_mul_f32 v[36:37], v[22:23], v[0:1] op_sel_hi:[1,0]
	v_pk_mul_f32 v[22:23], v[32:33], v[0:1] op_sel_hi:[1,0]
	v_pk_mul_f32 v[24:25], v[30:31], v[0:1] op_sel_hi:[1,0]
	s_and_b64 vcc, exec, s[44:45]
	v_pk_mul_f32 v[18:19], v[18:19], v[0:1] op_sel_hi:[1,0]
	v_cvt_pk_bf16_f32 v40, v46, v47
	v_cvt_pk_bf16_f32 v41, v38, v39
	global_store_dwordx4 v[48:49], v[40:43], off offset:64
	s_cbranch_vccnz .LBB0_447
	v_mov_b32_e32 v32, v35
	v_mov_b32_e32 v33, v37
	v_mov_b32_e32 v30, v34
	v_mov_b32_e32 v31, v36
	v_pk_mul_f32 v[32:33], v[32:33], v[32:33]
	v_mov_b32_e32 v38, v19
	v_pk_fma_f32 v[30:31], v[30:31], v[30:31], v[32:33]
	v_mov_b32_e32 v32, v28
	v_mov_b32_e32 v33, v26
	v_pk_fma_f32 v[30:31], v[32:33], v[32:33], v[30:31]
	v_mov_b32_e32 v32, v29
	v_mov_b32_e32 v33, v27
	v_mov_b32_e32 v39, v25
	v_pk_fma_f32 v[30:31], v[32:33], v[32:33], v[30:31]
	v_mov_b32_e32 v32, v18
	v_mov_b32_e32 v33, v24
	v_pk_mul_f32 v[38:39], v[38:39], v[38:39]
	v_add_f32_e32 v0, v30, v31
	v_pk_fma_f32 v[32:33], v[32:33], v[32:33], v[38:39]
	v_mov_b32_e32 v38, v20
	v_mov_b32_e32 v39, v22
	v_and_b32_e32 v31, 64, v224
	v_pk_fma_f32 v[32:33], v[38:39], v[38:39], v[32:33]
	v_mov_b32_e32 v38, v21
	v_mov_b32_e32 v39, v23
	v_xor_b32_e32 v30, 16, v224
	v_add_u32_e32 v31, 64, v31
	v_pk_fma_f32 v[32:33], v[38:39], v[38:39], v[32:33]
	v_cmp_lt_i32_e32 vcc, v30, v31
	v_add_f32_e32 v0, v33, v0
	v_add_f32_e32 v0, v32, v0
	v_cndmask_b32_e32 v30, v224, v30, vcc
	v_lshlrev_b32_e32 v30, 2, v30
	ds_bpermute_b32 v30, v30, v0
	v_pk_mul_f32 v[12:13], v[22:23], v[12:13]
	v_pk_mul_f32 v[10:11], v[24:25], v[10:11]
	v_pk_mul_f32 v[16:17], v[28:29], v[16:17]
	v_pk_mul_f32 v[14:15], v[34:35], v[14:15]
	s_waitcnt lgkmcnt(0)
	v_add_f32_e32 v0, v0, v30
	v_xor_b32_e32 v30, 32, v224
	v_cmp_lt_i32_e32 vcc, v30, v31
	v_pk_mul_f32 v[4:5], v[20:21], v[4:5]
	v_pk_mul_f32 v[2:3], v[18:19], v[2:3]
	v_cndmask_b32_e32 v30, v224, v30, vcc
	v_lshlrev_b32_e32 v30, 2, v30
	ds_bpermute_b32 v30, v30, v0
	v_pk_mul_f32 v[8:9], v[26:27], v[8:9]
	v_pk_mul_f32 v[6:7], v[36:37], v[6:7]
	s_waitcnt lgkmcnt(0)
	v_add_f32_e32 v0, v0, v30
	v_fmamk_f32 v0, v0, 0x3c800000, v227
	v_mul_f32_e32 v30, 0x4b800000, v0
	v_cmp_gt_f32_e32 vcc, s16, v0
	s_nop 1
	v_cndmask_b32_e32 v0, v0, v30, vcc
	v_rsq_f32_e32 v0, v0
	s_nop 0
	v_mul_f32_e32 v30, 0x45800000, v0
	v_cndmask_b32_e32 v0, v0, v30, vcc
	v_mul_f32_e32 v30, 0x3e38aa3b, v0
	v_cndmask_b32_e64 v0, v0, v30, s[96:97]
	v_pk_mul_f32 v[12:13], v[12:13], v[0:1] op_sel_hi:[1,0]
	v_pk_mul_f32 v[10:11], v[10:11], v[0:1] op_sel_hi:[1,0]
	v_pk_mul_f32 v[14:15], v[14:15], v[0:1] op_sel_hi:[1,0]
	v_pk_mul_f32 v[16:17], v[16:17], v[0:1] op_sel_hi:[1,0]
	s_waitcnt vmcnt(2)
	v_pk_mul_f32 v[22:23], v[94:95], v[10:11]
	v_pk_mul_f32 v[24:25], v[96:97], v[12:13]
	v_pk_fma_f32 v[34:35], v[86:87], v[14:15], v[22:23] neg_lo:[0,0,1] neg_hi:[0,0,1]
	v_pk_fma_f32 v[28:29], v[88:89], v[16:17], v[24:25] neg_lo:[0,0,1] neg_hi:[0,0,1]
	v_pk_mul_f32 v[14:15], v[94:95], v[14:15]
	v_pk_mul_f32 v[16:17], v[96:97], v[16:17]
	v_pk_mul_f32 v[4:5], v[4:5], v[0:1] op_sel_hi:[1,0]
	v_pk_mul_f32 v[2:3], v[2:3], v[0:1] op_sel_hi:[1,0]
	v_pk_fma_f32 v[22:23], v[88:89], v[12:13], v[16:17]
	v_pk_fma_f32 v[24:25], v[86:87], v[10:11], v[14:15]
	v_pk_mul_f32 v[6:7], v[6:7], v[0:1] op_sel_hi:[1,0]
	v_pk_mul_f32 v[8:9], v[8:9], v[0:1] op_sel_hi:[1,0]
	v_pk_mul_f32 v[10:11], v[78:79], v[2:3]
	v_pk_mul_f32 v[12:13], v[80:81], v[4:5]
	v_pk_fma_f32 v[36:37], v[66:67], v[6:7], v[10:11] neg_lo:[0,0,1] neg_hi:[0,0,1]
	v_pk_fma_f32 v[26:27], v[68:69], v[8:9], v[12:13] neg_lo:[0,0,1] neg_hi:[0,0,1]
	v_pk_mul_f32 v[6:7], v[78:79], v[6:7]
	v_pk_mul_f32 v[8:9], v[80:81], v[8:9]
	v_pk_fma_f32 v[18:19], v[66:67], v[2:3], v[6:7]
	v_pk_fma_f32 v[20:21], v[68:69], v[4:5], v[8:9]
	s_branch .LBB0_447
